# LN1/router phase: stage_router 8 loads issued together; router logits loop: 32 A-fragment loads issued up front with counted vmcnt instead of one load + vmcnt(0) per k-step (on top of DPP reductions)
# speedup vs baseline: 1.0096x; 1.0060x over previous
; #define LAS __attribute__((address_space(3)))
; __device__ __forceinline__ unsigned cvt_pk_bf16(float lo, float hi) { unsigned r; asm volatile("v_cvt_pk_bf16_f32 %0, %1, %2" : "=v"(r) : "v"(lo), "v"(hi)); return r; }
; __device__ __forceinline__ void stage_router(const float* wr, LAS bf16_t* wH, int tid) {
;     LAS bf16_t* wL = wH + NE * RW_LD;
;     for (int i = tid; i < D_ * NE / 4; i += 512) { const f32x4 q = *(const f32x4*)(wr + 4 * i); const int k = i >> 2, e0 = (i & 3) * 4; const float v[4] = {q.x, q.y, q.z, q.w};
; #pragma unroll
;         for (int c = 0; c < 4; ++c) { const unsigned hi = cvt_pk_bf16(v[c], 0.f) & 0xffffu; const unsigned lo = cvt_pk_bf16(v[c] - __uint_as_float(hi << 16), 0.f) & 0xffffu;
;             wH[(e0 + c) * RW_LD + k] = (bf16_t)hi; wL[(e0 + c) * RW_LD + k] = (bf16_t)lo; } }
.LBB0_564:
	s_andn2_b64 vcc, exec, s[0:1]
	s_cbranch_vccnz .LBB0_642
	v_readlane_b32 s6, v254, 0
	v_readlane_b32 s7, v254, 1
	v_mov_b32_e32 v0, v222
	s_lshl_b32 s86, s82, 10
	v_readfirstlane_b32 s20, v0
	v_cmp_gt_i32_e32 vcc, s33, v0
	s_and_saveexec_b64 s[0:1], vcc
	s_cbranch_execz .LBB0_568
	s_load_dwordx2 s[4:5], s[6:7], 0x80
	s_lshl_b64 s[8:9], s[86:87], 6
	v_lshlrev_b32_e32 v2, 2, v0
	v_mov_b32_e32 v1, v0
	s_waitcnt lgkmcnt(0)
	s_add_u32 s4, s4, s8
	s_addc_u32 s5, s5, s9
	s_mov_b64 s[8:9], 0
	v_mov_b32_e32 v44, v2
	v_ashrrev_i32_e32 v45, 31, v44
	v_lshl_add_u64 v[46:47], v[44:45], 2, s[4:5]
	global_load_dwordx4 v[12:15], v[46:47], off
	v_add_u32_e32 v44, 0x800, v2
	v_ashrrev_i32_e32 v45, 31, v44
	v_lshl_add_u64 v[46:47], v[44:45], 2, s[4:5]
	global_load_dwordx4 v[16:19], v[46:47], off
	v_add_u32_e32 v44, 0x1000, v2
	v_ashrrev_i32_e32 v45, 31, v44
	v_lshl_add_u64 v[46:47], v[44:45], 2, s[4:5]
	global_load_dwordx4 v[20:23], v[46:47], off
	v_add_u32_e32 v44, 0x1800, v2
	v_ashrrev_i32_e32 v45, 31, v44
	v_lshl_add_u64 v[46:47], v[44:45], 2, s[4:5]
	global_load_dwordx4 v[24:27], v[46:47], off
	v_add_u32_e32 v44, 0x2000, v2
	v_ashrrev_i32_e32 v45, 31, v44
	v_lshl_add_u64 v[46:47], v[44:45], 2, s[4:5]
	global_load_dwordx4 v[28:31], v[46:47], off
	v_add_u32_e32 v44, 0x2800, v2
	v_ashrrev_i32_e32 v45, 31, v44
	v_lshl_add_u64 v[46:47], v[44:45], 2, s[4:5]
	global_load_dwordx4 v[32:35], v[46:47], off
	v_add_u32_e32 v44, 0x3000, v2
	v_ashrrev_i32_e32 v45, 31, v44
	v_lshl_add_u64 v[46:47], v[44:45], 2, s[4:5]
	global_load_dwordx4 v[36:39], v[46:47], off
	v_add_u32_e32 v44, 0x3800, v2
	v_ashrrev_i32_e32 v45, 31, v44
	v_lshl_add_u64 v[46:47], v[44:45], 2, s[4:5]
	global_load_dwordx4 v[40:43], v[46:47], off
	s_movk_i32 s10, 0x408
	v_mov_b32_e32 v1, v0
	v_mov_b32_e32 v8, v2
	v_ashrrev_i32_e32 v3, 2, v1
	v_and_b32_e32 v8, 12, v8
	v_mad_u32_u24 v3, v8, s10, v3
	v_lshl_add_u32 v3, v3, 1, 0
	s_waitcnt vmcnt(7)
	v_cvt_pk_bf16_f32 v9, v12, v195
	s_nop 0
	v_lshlrev_b32_e32 v10, 16, v9
	v_sub_f32_e32 v10, v12, v10
	v_cvt_pk_bf16_f32 v10, v10, v195
	s_nop 0
	ds_write_b16 v3, v9
	ds_write_b16 v3, v10 offset:33024
	v_cvt_pk_bf16_f32 v9, v13, v195
	s_nop 0
	v_lshlrev_b32_e32 v10, 16, v9
	v_sub_f32_e32 v10, v13, v10
	v_cvt_pk_bf16_f32 v10, v10, v195
	s_nop 0
	ds_write_b16 v3, v9 offset:2064
	ds_write_b16 v3, v10 offset:35088
	v_cvt_pk_bf16_f32 v9, v14, v195
	s_nop 0
	v_lshlrev_b32_e32 v10, 16, v9
	v_sub_f32_e32 v10, v14, v10
	v_cvt_pk_bf16_f32 v10, v10, v195
	s_nop 0
	ds_write_b16 v3, v9 offset:4128
	ds_write_b16 v3, v10 offset:37152
	v_cvt_pk_bf16_f32 v9, v15, v195
	s_nop 0
	v_lshlrev_b32_e32 v10, 16, v9
	v_sub_f32_e32 v10, v15, v10
	v_cvt_pk_bf16_f32 v10, v10, v195
	s_nop 0
	ds_write_b16 v3, v9 offset:6192
	ds_write_b16 v3, v10 offset:39216
	v_add_u32_e32 v1, 0x200, v0
	v_add_u32_e32 v8, 0x800, v2
	v_ashrrev_i32_e32 v3, 2, v1
	v_and_b32_e32 v8, 12, v8
	v_mad_u32_u24 v3, v8, s10, v3
	v_lshl_add_u32 v3, v3, 1, 0
	s_waitcnt vmcnt(6)
	v_cvt_pk_bf16_f32 v9, v16, v195
	s_nop 0
	v_lshlrev_b32_e32 v10, 16, v9
	v_sub_f32_e32 v10, v16, v10
	v_cvt_pk_bf16_f32 v10, v10, v195
	s_nop 0
	ds_write_b16 v3, v9
	ds_write_b16 v3, v10 offset:33024
	v_cvt_pk_bf16_f32 v9, v17, v195
	s_nop 0
	v_lshlrev_b32_e32 v10, 16, v9
	v_sub_f32_e32 v10, v17, v10
	v_cvt_pk_bf16_f32 v10, v10, v195
	s_nop 0
	ds_write_b16 v3, v9 offset:2064
	ds_write_b16 v3, v10 offset:35088
	v_cvt_pk_bf16_f32 v9, v18, v195
	s_nop 0
	v_lshlrev_b32_e32 v10, 16, v9
	v_sub_f32_e32 v10, v18, v10
	v_cvt_pk_bf16_f32 v10, v10, v195
	s_nop 0
	ds_write_b16 v3, v9 offset:4128
	ds_write_b16 v3, v10 offset:37152
	v_cvt_pk_bf16_f32 v9, v19, v195
	s_nop 0
	v_lshlrev_b32_e32 v10, 16, v9
	v_sub_f32_e32 v10, v19, v10
	v_cvt_pk_bf16_f32 v10, v10, v195
	s_nop 0
	ds_write_b16 v3, v9 offset:6192
	ds_write_b16 v3, v10 offset:39216
	v_add_u32_e32 v1, 0x400, v0
	v_add_u32_e32 v8, 0x1000, v2
	v_ashrrev_i32_e32 v3, 2, v1
	v_and_b32_e32 v8, 12, v8
	v_mad_u32_u24 v3, v8, s10, v3
	v_lshl_add_u32 v3, v3, 1, 0
	s_waitcnt vmcnt(5)
	v_cvt_pk_bf16_f32 v9, v20, v195
	s_nop 0
	v_lshlrev_b32_e32 v10, 16, v9
	v_sub_f32_e32 v10, v20, v10
	v_cvt_pk_bf16_f32 v10, v10, v195
	s_nop 0
	ds_write_b16 v3, v9
	ds_write_b16 v3, v10 offset:33024
	v_cvt_pk_bf16_f32 v9, v21, v195
	s_nop 0
	v_lshlrev_b32_e32 v10, 16, v9
	v_sub_f32_e32 v10, v21, v10
	v_cvt_pk_bf16_f32 v10, v10, v195
	s_nop 0
	ds_write_b16 v3, v9 offset:2064
	ds_write_b16 v3, v10 offset:35088
	v_cvt_pk_bf16_f32 v9, v22, v195
	s_nop 0
	v_lshlrev_b32_e32 v10, 16, v9
	v_sub_f32_e32 v10, v22, v10
	v_cvt_pk_bf16_f32 v10, v10, v195
	s_nop 0
	ds_write_b16 v3, v9 offset:4128
	ds_write_b16 v3, v10 offset:37152
	v_cvt_pk_bf16_f32 v9, v23, v195
	s_nop 0
	v_lshlrev_b32_e32 v10, 16, v9
	v_sub_f32_e32 v10, v23, v10
	v_cvt_pk_bf16_f32 v10, v10, v195
	s_nop 0
	ds_write_b16 v3, v9 offset:6192
	ds_write_b16 v3, v10 offset:39216
	v_add_u32_e32 v1, 0x600, v0
	v_add_u32_e32 v8, 0x1800, v2
	v_ashrrev_i32_e32 v3, 2, v1
	v_and_b32_e32 v8, 12, v8
	v_mad_u32_u24 v3, v8, s10, v3
	v_lshl_add_u32 v3, v3, 1, 0
	s_waitcnt vmcnt(4)
; #define LAS __attribute__((address_space(3)))
; __device__ __forceinline__ unsigned cvt_pk_bf16(float lo, float hi) { unsigned r; asm volatile("v_cvt_pk_bf16_f32 %0, %1, %2" : "=v"(r) : "v"(lo), "v"(hi)); return r; }
; __device__ __forceinline__ void stage_router(const float* wr, LAS bf16_t* wH, int tid) {
;     LAS bf16_t* wL = wH + NE * RW_LD;
;     for (int i = tid; i < D_ * NE / 4; i += 512) { const f32x4 q = *(const f32x4*)(wr + 4 * i); const int k = i >> 2, e0 = (i & 3) * 4; const float v[4] = {q.x, q.y, q.z, q.w};
; #pragma unroll
;         for (int c = 0; c < 4; ++c) { const unsigned hi = cvt_pk_bf16(v[c], 0.f) & 0xffffu; const unsigned lo = cvt_pk_bf16(v[c] - __uint_as_float(hi << 16), 0.f) & 0xffffu;
;             wH[(e0 + c) * RW_LD + k] = (bf16_t)hi; wL[(e0 + c) * RW_LD + k] = (bf16_t)lo; } }
	v_cvt_pk_bf16_f32 v9, v24, v195
	s_nop 0
	v_lshlrev_b32_e32 v10, 16, v9
	v_sub_f32_e32 v10, v24, v10
	v_cvt_pk_bf16_f32 v10, v10, v195
	s_nop 0
	ds_write_b16 v3, v9
	ds_write_b16 v3, v10 offset:33024
	v_cvt_pk_bf16_f32 v9, v25, v195
	s_nop 0
	v_lshlrev_b32_e32 v10, 16, v9
	v_sub_f32_e32 v10, v25, v10
	v_cvt_pk_bf16_f32 v10, v10, v195
	s_nop 0
	ds_write_b16 v3, v9 offset:2064
	ds_write_b16 v3, v10 offset:35088
	v_cvt_pk_bf16_f32 v9, v26, v195
	s_nop 0
	v_lshlrev_b32_e32 v10, 16, v9
	v_sub_f32_e32 v10, v26, v10
	v_cvt_pk_bf16_f32 v10, v10, v195
	s_nop 0
	ds_write_b16 v3, v9 offset:4128
	ds_write_b16 v3, v10 offset:37152
	v_cvt_pk_bf16_f32 v9, v27, v195
	s_nop 0
	v_lshlrev_b32_e32 v10, 16, v9
	v_sub_f32_e32 v10, v27, v10
	v_cvt_pk_bf16_f32 v10, v10, v195
	s_nop 0
	ds_write_b16 v3, v9 offset:6192
	ds_write_b16 v3, v10 offset:39216
	v_add_u32_e32 v1, 0x800, v0
	v_add_u32_e32 v8, 0x2000, v2
	v_ashrrev_i32_e32 v3, 2, v1
	v_and_b32_e32 v8, 12, v8
	v_mad_u32_u24 v3, v8, s10, v3
	v_lshl_add_u32 v3, v3, 1, 0
	s_waitcnt vmcnt(3)
	v_cvt_pk_bf16_f32 v9, v28, v195
	s_nop 0
	v_lshlrev_b32_e32 v10, 16, v9
	v_sub_f32_e32 v10, v28, v10
	v_cvt_pk_bf16_f32 v10, v10, v195
	s_nop 0
	ds_write_b16 v3, v9
	ds_write_b16 v3, v10 offset:33024
	v_cvt_pk_bf16_f32 v9, v29, v195
	s_nop 0
	v_lshlrev_b32_e32 v10, 16, v9
	v_sub_f32_e32 v10, v29, v10
	v_cvt_pk_bf16_f32 v10, v10, v195
	s_nop 0
	ds_write_b16 v3, v9 offset:2064
	ds_write_b16 v3, v10 offset:35088
	v_cvt_pk_bf16_f32 v9, v30, v195
	s_nop 0
	v_lshlrev_b32_e32 v10, 16, v9
	v_sub_f32_e32 v10, v30, v10
	v_cvt_pk_bf16_f32 v10, v10, v195
	s_nop 0
	ds_write_b16 v3, v9 offset:4128
	ds_write_b16 v3, v10 offset:37152
	v_cvt_pk_bf16_f32 v9, v31, v195
	s_nop 0
	v_lshlrev_b32_e32 v10, 16, v9
	v_sub_f32_e32 v10, v31, v10
	v_cvt_pk_bf16_f32 v10, v10, v195
	s_nop 0
	ds_write_b16 v3, v9 offset:6192
	ds_write_b16 v3, v10 offset:39216
	v_add_u32_e32 v1, 0xa00, v0
	v_add_u32_e32 v8, 0x2800, v2
	v_ashrrev_i32_e32 v3, 2, v1
	v_and_b32_e32 v8, 12, v8
	v_mad_u32_u24 v3, v8, s10, v3
	v_lshl_add_u32 v3, v3, 1, 0
	s_waitcnt vmcnt(2)
	v_cvt_pk_bf16_f32 v9, v32, v195
	s_nop 0
	v_lshlrev_b32_e32 v10, 16, v9
	v_sub_f32_e32 v10, v32, v10
	v_cvt_pk_bf16_f32 v10, v10, v195
	s_nop 0
	ds_write_b16 v3, v9
	ds_write_b16 v3, v10 offset:33024
	v_cvt_pk_bf16_f32 v9, v33, v195
	s_nop 0
	v_lshlrev_b32_e32 v10, 16, v9
	v_sub_f32_e32 v10, v33, v10
	v_cvt_pk_bf16_f32 v10, v10, v195
	s_nop 0
	ds_write_b16 v3, v9 offset:2064
	ds_write_b16 v3, v10 offset:35088
	v_cvt_pk_bf16_f32 v9, v34, v195
	s_nop 0
	v_lshlrev_b32_e32 v10, 16, v9
	v_sub_f32_e32 v10, v34, v10
	v_cvt_pk_bf16_f32 v10, v10, v195
	s_nop 0
	ds_write_b16 v3, v9 offset:4128
	ds_write_b16 v3, v10 offset:37152
	v_cvt_pk_bf16_f32 v9, v35, v195
	s_nop 0
	v_lshlrev_b32_e32 v10, 16, v9
	v_sub_f32_e32 v10, v35, v10
	v_cvt_pk_bf16_f32 v10, v10, v195
	s_nop 0
	ds_write_b16 v3, v9 offset:6192
	ds_write_b16 v3, v10 offset:39216
	v_add_u32_e32 v1, 0xc00, v0
	v_add_u32_e32 v8, 0x3000, v2
	v_ashrrev_i32_e32 v3, 2, v1
	v_and_b32_e32 v8, 12, v8
	v_mad_u32_u24 v3, v8, s10, v3
	v_lshl_add_u32 v3, v3, 1, 0
	s_waitcnt vmcnt(1)
	v_cvt_pk_bf16_f32 v9, v36, v195
	s_nop 0
	v_lshlrev_b32_e32 v10, 16, v9
	v_sub_f32_e32 v10, v36, v10
	v_cvt_pk_bf16_f32 v10, v10, v195
	s_nop 0
	ds_write_b16 v3, v9
	ds_write_b16 v3, v10 offset:33024
	v_cvt_pk_bf16_f32 v9, v37, v195
	s_nop 0
	v_lshlrev_b32_e32 v10, 16, v9
	v_sub_f32_e32 v10, v37, v10
	v_cvt_pk_bf16_f32 v10, v10, v195
	s_nop 0
	ds_write_b16 v3, v9 offset:2064
	ds_write_b16 v3, v10 offset:35088
	v_cvt_pk_bf16_f32 v9, v38, v195
	s_nop 0
	v_lshlrev_b32_e32 v10, 16, v9
	v_sub_f32_e32 v10, v38, v10
	v_cvt_pk_bf16_f32 v10, v10, v195
	s_nop 0
	ds_write_b16 v3, v9 offset:4128
	ds_write_b16 v3, v10 offset:37152
	v_cvt_pk_bf16_f32 v9, v39, v195
	s_nop 0
	v_lshlrev_b32_e32 v10, 16, v9
	v_sub_f32_e32 v10, v39, v10
	v_cvt_pk_bf16_f32 v10, v10, v195
	s_nop 0
	ds_write_b16 v3, v9 offset:6192
	ds_write_b16 v3, v10 offset:39216
	v_add_u32_e32 v1, 0xe00, v0
	v_add_u32_e32 v8, 0x3800, v2
	v_ashrrev_i32_e32 v3, 2, v1
	v_and_b32_e32 v8, 12, v8
	v_mad_u32_u24 v3, v8, s10, v3
	v_lshl_add_u32 v3, v3, 1, 0
	s_waitcnt vmcnt(0)
	v_cvt_pk_bf16_f32 v9, v40, v195
	s_nop 0
	v_lshlrev_b32_e32 v10, 16, v9
	v_sub_f32_e32 v10, v40, v10
	v_cvt_pk_bf16_f32 v10, v10, v195
	s_nop 0
	ds_write_b16 v3, v9
	ds_write_b16 v3, v10 offset:33024
	v_cvt_pk_bf16_f32 v9, v41, v195
	s_nop 0
	v_lshlrev_b32_e32 v10, 16, v9
	v_sub_f32_e32 v10, v41, v10
	v_cvt_pk_bf16_f32 v10, v10, v195
	s_nop 0
	ds_write_b16 v3, v9 offset:2064
	ds_write_b16 v3, v10 offset:35088
	v_cvt_pk_bf16_f32 v9, v42, v195
	s_nop 0
	v_lshlrev_b32_e32 v10, 16, v9
	v_sub_f32_e32 v10, v42, v10
	v_cvt_pk_bf16_f32 v10, v10, v195
	s_nop 0
	ds_write_b16 v3, v9 offset:4128
	ds_write_b16 v3, v10 offset:37152
	v_cvt_pk_bf16_f32 v9, v43, v195
	s_nop 0
	v_lshlrev_b32_e32 v10, 16, v9
	v_sub_f32_e32 v10, v43, v10
	v_cvt_pk_bf16_f32 v10, v10, v195
	s_nop 0
	ds_write_b16 v3, v9 offset:6192
	ds_write_b16 v3, v10 offset:39216

; __device__ __forceinline__ float bf_lo(unsigned u) { return __uint_as_float(u << 16); }
; __device__ __forceinline__ float bf_hi(unsigned u) { return __uint_as_float(u & 0xffff0000u); }
; __device__ __forceinline__ void ln1_router_tile(KArgs A, int l, int tile, int lane, const LAS bf16_t* wH) {
;     ...
; #pragma unroll 1
;     for (int r0 = 0; r0 < 16; r0 += 8) {
;         u32x2 hr[8][4], mm[8][4];
; #pragma unroll
;         for (int i = 0; i < 8; ++i) {
; #pragma unroll
;             for (int j = 0; j < 4; ++j) { hr[i][j] = *(const u32x2*)(HB + (size_t)(r0 + i) * D_ + 4 * lane + 256 * j); mm[i][j] = __builtin_nontemporal_load((const u32x2*)(mix + (size_t)(r0 + i) * D_ + 4 * lane + 256 * j)); } }
; #pragma unroll
;         for (int i = 0; i < 8; ++i) { f32x4 hv[4];
; #pragma unroll
;             for (int j = 0; j < 4; ++j) { hv[j].x = bf_lo(hr[i][j].x) * ALPHA_ + bf_lo(mm[i][j].x); hv[j].y = bf_hi(hr[i][j].x) * ALPHA_ + bf_hi(mm[i][j].x); hv[j].z = bf_lo(hr[i][j].y) * ALPHA_ + bf_lo(mm[i][j].y); hv[j].w = bf_hi(hr[i][j].y) * ALPHA_ + bf_hi(mm[i][j].y); }
.LBB0_584:
	s_lshl_b64 s[26:27], s[86:87], 1
	v_lshl_add_u64 v[118:119], v[0:1], 0, s[26:27]
	v_lshl_add_u64 v[10:11], v[2:3], 0, s[26:27]
	global_load_dwordx2 v[150:151], v[118:119], off
	global_load_dwordx2 v[148:149], v[10:11], off nt
	global_load_dwordx2 v[146:147], v[118:119], off offset:512
	global_load_dwordx2 v[144:145], v[10:11], off offset:512 nt
	global_load_dwordx2 v[142:143], v[118:119], off offset:1024
	global_load_dwordx2 v[140:141], v[10:11], off offset:1024 nt
	global_load_dwordx2 v[136:137], v[118:119], off offset:1536
	global_load_dwordx2 v[138:139], v[10:11], off offset:1536 nt
	global_load_dwordx2 v[134:135], v[118:119], off offset:2048
	global_load_dwordx2 v[132:133], v[10:11], off offset:2048 nt
	global_load_dwordx2 v[130:131], v[118:119], off offset:2560
	global_load_dwordx2 v[128:129], v[10:11], off offset:2560 nt
	global_load_dwordx2 v[126:127], v[118:119], off offset:3072
	global_load_dwordx2 v[124:125], v[10:11], off offset:3072 nt
	global_load_dwordx2 v[120:121], v[118:119], off offset:3584
	global_load_dwordx2 v[122:123], v[10:11], off offset:3584 nt
	v_cndmask_b32_e64 v9, 0, 1, s[8:9]
	v_cmp_ne_u32_e64 s[6:7], 1, v9
	s_or_b32 s0, s86, 0x800
	s_mov_b32 s1, s87
	s_lshl_b64 s[20:21], s[0:1], 1
	s_or_b32 s0, s86, 0xc00
	s_lshl_b64 s[18:19], s[0:1], 1
	s_or_b32 s0, s86, 0x1000
	v_lshl_add_u64 v[100:101], v[0:1], 0, s[20:21]
	v_lshl_add_u64 v[10:11], v[2:3], 0, s[20:21]
	s_lshl_b64 s[16:17], s[0:1], 1
	s_or_b32 s0, s86, 0x1400
	global_load_dwordx2 v[116:117], v[100:101], off
	global_load_dwordx2 v[114:115], v[10:11], off nt
	global_load_dwordx2 v[112:113], v[100:101], off offset:512
	global_load_dwordx2 v[110:111], v[10:11], off offset:512 nt
	global_load_dwordx2 v[108:109], v[100:101], off offset:1024
	global_load_dwordx2 v[106:107], v[10:11], off offset:1024 nt
	global_load_dwordx2 v[104:105], v[100:101], off offset:1536
	global_load_dwordx2 v[102:103], v[10:11], off offset:1536 nt
	v_lshl_add_u64 v[82:83], v[0:1], 0, s[18:19]
	v_lshl_add_u64 v[10:11], v[2:3], 0, s[18:19]
	s_lshl_b64 s[8:9], s[0:1], 1
	global_load_dwordx2 v[98:99], v[82:83], off
	global_load_dwordx2 v[96:97], v[10:11], off nt
	global_load_dwordx2 v[94:95], v[82:83], off offset:512
	global_load_dwordx2 v[92:93], v[10:11], off offset:512 nt
	global_load_dwordx2 v[90:91], v[82:83], off offset:1024
	global_load_dwordx2 v[88:89], v[10:11], off offset:1024 nt
	global_load_dwordx2 v[86:87], v[82:83], off offset:1536
	global_load_dwordx2 v[84:85], v[10:11], off offset:1536 nt
	v_lshl_add_u64 v[64:65], v[0:1], 0, s[16:17]
	v_lshl_add_u64 v[10:11], v[2:3], 0, s[16:17]
	global_load_dwordx2 v[80:81], v[64:65], off
	global_load_dwordx2 v[78:79], v[10:11], off nt
	global_load_dwordx2 v[76:77], v[64:65], off offset:512
	global_load_dwordx2 v[74:75], v[10:11], off offset:512 nt
	global_load_dwordx2 v[72:73], v[64:65], off offset:1024
	global_load_dwordx2 v[70:71], v[10:11], off offset:1024 nt
	global_load_dwordx2 v[68:69], v[64:65], off offset:1536
	global_load_dwordx2 v[66:67], v[10:11], off offset:1536 nt
	v_lshl_add_u64 v[46:47], v[0:1], 0, s[8:9]
	v_lshl_add_u64 v[10:11], v[2:3], 0, s[8:9]
	s_or_b32 s0, s86, 0x1800
	s_lshl_b64 s[4:5], s[0:1], 1
	s_or_b32 s86, s86, 0x1c00
	s_lshl_b64 s[0:1], s[86:87], 1
	global_load_dwordx2 v[62:63], v[46:47], off
	global_load_dwordx2 v[60:61], v[10:11], off nt
	global_load_dwordx2 v[58:59], v[46:47], off offset:512
	global_load_dwordx2 v[56:57], v[10:11], off offset:512 nt
	global_load_dwordx2 v[54:55], v[46:47], off offset:1024
	global_load_dwordx2 v[52:53], v[10:11], off offset:1024 nt
	global_load_dwordx2 v[50:51], v[46:47], off offset:1536
	global_load_dwordx2 v[48:49], v[10:11], off offset:1536 nt
	v_lshl_add_u64 v[28:29], v[0:1], 0, s[4:5]
	v_lshl_add_u64 v[10:11], v[2:3], 0, s[4:5]
	global_load_dwordx2 v[44:45], v[28:29], off
	global_load_dwordx2 v[42:43], v[10:11], off nt
	global_load_dwordx2 v[40:41], v[28:29], off offset:512
	global_load_dwordx2 v[38:39], v[10:11], off offset:512 nt
	global_load_dwordx2 v[36:37], v[28:29], off offset:1024
	global_load_dwordx2 v[34:35], v[10:11], off offset:1024 nt
	global_load_dwordx2 v[32:33], v[28:29], off offset:1536
	global_load_dwordx2 v[30:31], v[10:11], off offset:1536 nt
	v_lshl_add_u64 v[10:11], v[0:1], 0, s[0:1]
	v_lshl_add_u64 v[12:13], v[2:3], 0, s[0:1]
	global_load_dwordx2 v[26:27], v[10:11], off
	global_load_dwordx2 v[24:25], v[12:13], off nt
	global_load_dwordx2 v[22:23], v[10:11], off offset:512
	global_load_dwordx2 v[20:21], v[12:13], off offset:512 nt
	global_load_dwordx2 v[18:19], v[10:11], off offset:1024
	global_load_dwordx2 v[16:17], v[12:13], off offset:1024 nt
	global_load_dwordx2 v[14:15], v[10:11], off offset:1536
	s_nop 0
	global_load_dwordx2 v[12:13], v[12:13], off offset:1536 nt
	s_movk_i32 s86, 0x2000
	s_waitcnt vmcnt(62)
	v_lshlrev_b32_e32 v162, 16, v150
	v_and_b32_e32 v163, 0xffff0000, v150
	v_lshlrev_b32_e32 v164, 16, v148
	v_and_b32_e32 v165, 0xffff0000, v148
	v_lshlrev_b32_e32 v150, 16, v151
	v_and_b32_e32 v151, 0xffff0000, v151
	v_lshlrev_b32_e32 v148, 16, v149
	v_and_b32_e32 v149, 0xffff0000, v149
	v_pk_fma_f32 v[162:163], v[162:163], s[78:79], v[164:165] op_sel_hi:[1,0,1]
	v_pk_fma_f32 v[148:149], v[150:151], s[78:79], v[148:149] op_sel_hi:[1,0,1]
	s_waitcnt vmcnt(61)
	v_lshlrev_b32_e32 v150, 16, v146
	v_and_b32_e32 v151, 0xffff0000, v146
	s_waitcnt vmcnt(60)
	v_lshlrev_b32_e32 v164, 16, v144
	v_and_b32_e32 v165, 0xffff0000, v144
	v_lshlrev_b32_e32 v146, 16, v147
	v_and_b32_e32 v147, 0xffff0000, v147
	v_lshlrev_b32_e32 v144, 16, v145
	v_and_b32_e32 v145, 0xffff0000, v145
	v_pk_fma_f32 v[150:151], v[150:151], s[78:79], v[164:165] op_sel_hi:[1,0,1]
	v_pk_fma_f32 v[144:145], v[146:147], s[78:79], v[144:145] op_sel_hi:[1,0,1]
	s_waitcnt vmcnt(59)
; #define LAS __attribute__((address_space(3)))
; __device__ __forceinline__ float bf_lo(unsigned u) { return __uint_as_float(u << 16); }
; __device__ __forceinline__ float bf_hi(unsigned u) { return __uint_as_float(u & 0xffff0000u); }
; __device__ __forceinline__ void ln_affine_l(f32x4 (&v)[4], const LAS float* gL, const LAS float* bL, int lane) {
;     float s = 0.f;
; #pragma unroll
;     for (int j = 0; j < 4; ++j) s += (v[j].x + v[j].y) + (v[j].z + v[j].w);
;     const float mean = wave_sum(s) * (1.f / D_); float s2 = 0.f;
; #pragma unroll
;     for (int j = 0; j < 4; ++j) { v[j] = v[j] - mean; s2 += (v[j].x * v[j].x + v[j].y * v[j].y) + (v[j].z * v[j].z + v[j].w * v[j].w); }
;     const float rstd = 1.f / sqrtf(wave_sum(s2) * (1.f / D_) + LN_EPS_);
; #pragma unroll
;     for (int j = 0; j < 4; ++j) v[j] = v[j] * rstd * *(const LAS f32x4*)(gL + 4 * lane + 256 * j) + *(const LAS f32x4*)(bL + 4 * lane + 256 * j);
; }
; __device__ __forceinline__ void ln1_router_tile(KArgs A, int l, int tile, int lane, const LAS bf16_t* wH) {
;     ...
;         for (int i = 0; i < 8; ++i) { f32x4 hv[4];
; #pragma unroll
;             for (int j = 0; j < 4; ++j) { hv[j].x = bf_lo(hr[i][j].x) * ALPHA_ + bf_lo(mm[i][j].x); hv[j].y = bf_hi(hr[i][j].x) * ALPHA_ + bf_hi(mm[i][j].x); hv[j].z = bf_lo(hr[i][j].y) * ALPHA_ + bf_lo(mm[i][j].y); hv[j].w = bf_hi(hr[i][j].y) * ALPHA_ + bf_hi(mm[i][j].y); }
;             ln_affine_l(hv, gL, bL, lane); store_row_bf16(HB + (size_t)(r0 + i) * D_, hv, lane); }
	v_lshlrev_b32_e32 v146, 16, v142
	v_and_b32_e32 v147, 0xffff0000, v142
	s_waitcnt vmcnt(58)
	v_lshlrev_b32_e32 v164, 16, v140
	v_and_b32_e32 v165, 0xffff0000, v140
	v_lshlrev_b32_e32 v142, 16, v143
	v_and_b32_e32 v143, 0xffff0000, v143
	v_lshlrev_b32_e32 v140, 16, v141
	v_and_b32_e32 v141, 0xffff0000, v141
	v_pk_fma_f32 v[146:147], v[146:147], s[78:79], v[164:165] op_sel_hi:[1,0,1]
	v_pk_fma_f32 v[164:165], v[142:143], s[78:79], v[140:141] op_sel_hi:[1,0,1]
	s_waitcnt vmcnt(57)
	v_lshlrev_b32_e32 v140, 16, v136
	v_and_b32_e32 v141, 0xffff0000, v136
	s_waitcnt vmcnt(56)
	v_lshlrev_b32_e32 v142, 16, v138
	v_and_b32_e32 v143, 0xffff0000, v138
	v_lshlrev_b32_e32 v136, 16, v137
	v_and_b32_e32 v137, 0xffff0000, v137
	v_lshlrev_b32_e32 v138, 16, v139
	v_and_b32_e32 v139, 0xffff0000, v139
	v_pk_fma_f32 v[168:169], v[136:137], s[78:79], v[138:139] op_sel_hi:[1,0,1]
	v_mov_b32_e32 v136, v162
	v_mov_b32_e32 v137, v148
	v_mov_b32_e32 v138, v163
	v_mov_b32_e32 v139, v149
	v_pk_fma_f32 v[166:167], v[140:141], s[78:79], v[142:143] op_sel_hi:[1,0,1]
	v_pk_add_f32 v[136:137], v[136:137], v[138:139]
	v_mov_b32_e32 v138, v150
	v_mov_b32_e32 v139, v144
	v_mov_b32_e32 v140, v151
	v_mov_b32_e32 v141, v145
	v_pk_add_f32 v[138:139], v[138:139], v[140:141]
	v_add_f32_e32 v9, v136, v137
	v_pk_add_f32 v[138:139], v[138:139], v[138:139] op_sel:[0,1] op_sel_hi:[1,0]
	v_pk_add_f32 v[140:141], v[146:147], v[146:147] op_sel:[0,1] op_sel_hi:[1,0]
	v_pk_add_f32 v[142:143], v[164:165], v[164:165] op_sel:[0,1] op_sel_hi:[1,0]
	v_add_f32_e32 v136, 0, v9
	v_mov_b32_e32 v137, v166
	v_mov_b32_e32 v139, v167
	v_mov_b32_e32 v141, v168
	v_mov_b32_e32 v143, v169
	v_pk_add_f32 v[136:137], v[136:137], v[138:139]
	v_pk_add_f32 v[138:139], v[140:141], v[142:143]
	s_nop 0
	v_pk_add_f32 v[136:137], v[136:137], v[138:139]
	s_nop 0
	v_add_f32_e32 v9, v136, v137
	s_waitcnt lgkmcnt(0)
	s_nop 1
	v_add_f32_dpp v9, v9, v9 quad_perm:[1,0,3,2] row_mask:0xf bank_mask:0xf
	s_waitcnt lgkmcnt(0)
	s_nop 1
	v_add_f32_dpp v9, v9, v9 quad_perm:[2,3,0,1] row_mask:0xf bank_mask:0xf
	s_waitcnt lgkmcnt(0)
	s_nop 1
	v_add_f32_dpp v9, v9, v9 row_half_mirror row_mask:0xf bank_mask:0xf
	s_waitcnt lgkmcnt(0)
	s_nop 1
	v_add_f32_dpp v9, v9, v9 row_mirror row_mask:0xf bank_mask:0xf
	s_waitcnt lgkmcnt(0)
	v_mov_b32_e32 v136, v9
	s_nop 1
	v_permlane16_swap_b32 v9, v136
	v_add_f32_e32 v9, v9, v136
	s_waitcnt lgkmcnt(0)
	v_mov_b32_e32 v136, v9
	s_nop 1
	v_permlane32_swap_b32 v9, v136
	v_add_f32_e32 v9, v9, v136
	v_fmamk_f32 v163, v9, 0xba800000, v163
	v_fmac_f32_e32 v162, 0xba800000, v9
	v_fmamk_f32 v149, v9, 0xba800000, v149
	v_fmac_f32_e32 v148, 0xba800000, v9
	v_pk_mul_f32 v[136:137], v[148:149], v[148:149]
	v_pk_mul_f32 v[138:139], v[162:163], v[162:163]
	v_fmamk_f32 v151, v9, 0xba800000, v151
	v_pk_mov_b32 v[140:141], v[138:139], v[136:137] op_sel:[1,0]
	v_mov_b32_e32 v139, v137
	v_pk_add_f32 v[136:137], v[140:141], v[138:139]
	v_fmac_f32_e32 v150, 0xba800000, v9
	v_fmamk_f32 v145, v9, 0xba800000, v145
	v_fmac_f32_e32 v144, 0xba800000, v9
	v_pk_add_f32 v[136:137], v[136:137], v[136:137] op_sel_hi:[0,1]
	v_pk_mul_f32 v[138:139], v[144:145], v[144:145]
	v_pk_mul_f32 v[140:141], v[150:151], v[150:151]
	v_fmac_f32_e32 v146, 0xba800000, v9
	v_pk_mov_b32 v[142:143], v[140:141], v[138:139] op_sel:[1,0]
	v_mov_b32_e32 v141, v139
	v_fmamk_f32 v147, v9, 0xba800000, v147
	v_fmac_f32_e32 v164, 0xba800000, v9
	v_mul_f32_e32 v136, v146, v146
	v_pk_add_f32 v[138:139], v[142:143], v[140:141]
	v_fmamk_f32 v165, v9, 0xba800000, v165
	v_pk_fma_f32 v[140:141], v[146:147], v[146:147], v[136:137] op_sel_hi:[1,1,0]
	v_mul_f32_e32 v136, v164, v164
	v_pk_add_f32 v[138:139], v[138:139], v[138:139] op_sel_hi:[0,1]
	v_pk_fma_f32 v[142:143], v[164:165], v[164:165], v[136:137] op_sel_hi:[1,1,0]
	v_fmamk_f32 v169, v9, 0xba800000, v169
	v_fmac_f32_e32 v168, 0xba800000, v9
	v_fmamk_f32 v167, v9, 0xba800000, v167
	v_fmac_f32_e32 v166, 0xba800000, v9
	v_mul_f32_e32 v140, v166, v166
	v_mul_f32_e32 v142, v167, v167
	v_mul_f32_e32 v136, v168, v168
	v_mul_f32_e32 v138, v169, v169
	v_pk_add_f32 v[140:141], v[140:141], v[142:143]
	v_pk_add_f32 v[136:137], v[136:137], v[138:139]
	s_nop 0
	v_pk_add_f32 v[136:137], v[140:141], v[136:137]
	s_nop 0
	v_add_f32_e32 v9, v136, v137
	s_waitcnt lgkmcnt(0)
	s_nop 1
	v_add_f32_dpp v9, v9, v9 quad_perm:[1,0,3,2] row_mask:0xf bank_mask:0xf
	s_waitcnt lgkmcnt(0)
	s_nop 1
	v_add_f32_dpp v9, v9, v9 quad_perm:[2,3,0,1] row_mask:0xf bank_mask:0xf
	s_waitcnt lgkmcnt(0)
	s_nop 1
	v_add_f32_dpp v9, v9, v9 row_half_mirror row_mask:0xf bank_mask:0xf
	s_waitcnt lgkmcnt(0)
	s_nop 1
	v_add_f32_dpp v9, v9, v9 row_mirror row_mask:0xf bank_mask:0xf
	s_waitcnt lgkmcnt(0)
	v_mov_b32_e32 v136, v9
	s_nop 1
	v_permlane16_swap_b32 v9, v136
	v_add_f32_e32 v9, v9, v136
	s_waitcnt lgkmcnt(0)
	v_mov_b32_e32 v136, v9
	s_nop 1
	v_permlane32_swap_b32 v9, v136
	v_add_f32_e32 v9, v9, v136
	v_fmamk_f32 v9, v9, 0x3a800000, v227
	v_cmp_gt_f32_e32 vcc, s47, v9
	v_mul_f32_e32 v136, 0x4f800000, v9
	s_nop 0
	v_cndmask_b32_e32 v9, v9, v136, vcc
	v_sqrt_f32_e32 v136, v9
	s_nop 0
	v_add_u32_e32 v137, -1, v136
	v_fma_f32 v138, -v137, v136, v9
	v_cmp_ge_f32_e64 s[8:9], 0, v138
	v_add_u32_e32 v138, 1, v136
	s_nop 0
	v_cndmask_b32_e64 v137, v136, v137, s[8:9]
	v_fma_f32 v136, -v138, v136, v9
	v_cmp_lt_f32_e64 s[8:9], 0, v136
	s_nop 1
	v_cndmask_b32_e64 v136, v137, v138, s[8:9]
	v_mul_f32_e32 v137, 0x37800000, v136
	v_cndmask_b32_e32 v136, v136, v137, vcc
	v_cmp_class_f32_e32 vcc, v9, v228
	s_nop 1
	v_cndmask_b32_e32 v9, v136, v9, vcc
	v_div_scale_f32 v136, s[0:1], v9, v9, 1.0
	v_rcp_f32_e32 v137, v136
	s_nop 0
	v_fma_f32 v138, -v136, v137, 1.0
	v_fmac_f32_e32 v137, v138, v137
	v_div_scale_f32 v138, vcc, 1.0, v9, 1.0
	v_mul_f32_e32 v139, v138, v137
	v_fma_f32 v140, -v136, v139, v138
	v_fmac_f32_e32 v139, v140, v137
	v_fma_f32 v136, -v136, v139, v138
	v_div_fmas_f32 v136, v136, v137, v139
	v_div_fixup_f32 v170, v136, v9, 1.0
	ds_read_b128 v[136:139], v152
	ds_read_b128 v[140:143], v153
	v_pk_mul_f32 v[162:163], v[162:163], v[170:171] op_sel_hi:[1,0]
	v_pk_mul_f32 v[148:149], v[148:149], v[170:171] op_sel_hi:[1,0]
	v_pk_mul_f32 v[150:151], v[150:151], v[170:171] op_sel_hi:[1,0]
	v_pk_mul_f32 v[144:145], v[144:145], v[170:171] op_sel_hi:[1,0]
	s_waitcnt lgkmcnt(0)
; #define LAS __attribute__((address_space(3)))
; __device__ __forceinline__ float bf_lo(unsigned u) { return __uint_as_float(u << 16); }
; __device__ __forceinline__ float bf_hi(unsigned u) { return __uint_as_float(u & 0xffff0000u); }
; __device__ __forceinline__ void ln_affine_l(f32x4 (&v)[4], const LAS float* gL, const LAS float* bL, int lane) {
;     float s = 0.f;
; #pragma unroll
;     for (int j = 0; j < 4; ++j) s += (v[j].x + v[j].y) + (v[j].z + v[j].w);
;     const float mean = wave_sum(s) * (1.f / D_); float s2 = 0.f;
; #pragma unroll
;     for (int j = 0; j < 4; ++j) { v[j] = v[j] - mean; s2 += (v[j].x * v[j].x + v[j].y * v[j].y) + (v[j].z * v[j].z + v[j].w * v[j].w); }
;     const float rstd = 1.f / sqrtf(wave_sum(s2) * (1.f / D_) + LN_EPS_);
; #pragma unroll
;     for (int j = 0; j < 4; ++j) v[j] = v[j] * rstd * *(const LAS f32x4*)(gL + 4 * lane + 256 * j) + *(const LAS f32x4*)(bL + 4 * lane + 256 * j);
; }
; __device__ __forceinline__ void ln1_router_tile(KArgs A, int l, int tile, int lane, const LAS bf16_t* wH) {
;     ...
;         for (int i = 0; i < 8; ++i) { f32x4 hv[4];
; #pragma unroll
;             for (int j = 0; j < 4; ++j) { hv[j].x = bf_lo(hr[i][j].x) * ALPHA_ + bf_lo(mm[i][j].x); hv[j].y = bf_hi(hr[i][j].x) * ALPHA_ + bf_hi(mm[i][j].x); hv[j].z = bf_lo(hr[i][j].y) * ALPHA_ + bf_lo(mm[i][j].y); hv[j].w = bf_hi(hr[i][j].y) * ALPHA_ + bf_hi(mm[i][j].y); }
;             ln_affine_l(hv, gL, bL, lane); store_row_bf16(HB + (size_t)(r0 + i) * D_, hv, lane); }
	v_pk_fma_f32 v[148:149], v[138:139], v[148:149], v[142:143]
	v_pk_fma_f32 v[162:163], v[136:137], v[162:163], v[140:141]
	ds_read_b128 v[136:139], v152 offset:1024
	ds_read_b128 v[140:143], v153 offset:1024
	v_pk_mul_f32 v[146:147], v[146:147], v[170:171] op_sel_hi:[1,0]
	v_pk_mul_f32 v[164:165], v[164:165], v[170:171] op_sel_hi:[1,0]
	v_pk_mul_f32 v[166:167], v[166:167], v[170:171] op_sel_hi:[1,0]
	v_pk_mul_f32 v[168:169], v[168:169], v[170:171] op_sel_hi:[1,0]
	s_waitcnt lgkmcnt(0)
	v_pk_fma_f32 v[144:145], v[138:139], v[144:145], v[142:143]
	v_pk_fma_f32 v[150:151], v[136:137], v[150:151], v[140:141]
	ds_read_b128 v[136:139], v152 offset:2048
	ds_read_b128 v[140:143], v153 offset:2048
	s_waitcnt lgkmcnt(0)
	v_pk_fma_f32 v[164:165], v[138:139], v[164:165], v[142:143]
	v_pk_fma_f32 v[146:147], v[136:137], v[146:147], v[140:141]
	ds_read_b128 v[136:139], v152 offset:3072
	ds_read_b128 v[140:143], v153 offset:3072
	s_waitcnt lgkmcnt(0)
	v_pk_fma_f32 v[136:137], v[136:137], v[166:167], v[140:141]
	v_cvt_pk_bf16_f32 v140, v162, v163
	v_cvt_pk_bf16_f32 v141, v148, v149
	global_store_dwordx2 v[118:119], v[140:141], off
	v_cvt_pk_bf16_f32 v140, v150, v151
	v_cvt_pk_bf16_f32 v141, v144, v145
	v_pk_fma_f32 v[138:139], v[138:139], v[168:169], v[142:143]
	global_store_dwordx2 v[118:119], v[140:141], off offset:512
	v_cvt_pk_bf16_f32 v140, v146, v147
	v_cvt_pk_bf16_f32 v141, v164, v165
	global_store_dwordx2 v[118:119], v[140:141], off offset:1024
	v_cvt_pk_bf16_f32 v136, v136, v137
	v_cvt_pk_bf16_f32 v137, v138, v139
	global_store_dwordx2 v[118:119], v[136:137], off offset:1536
	s_waitcnt vmcnt(59)
	v_lshlrev_b32_e32 v136, 16, v134
	v_and_b32_e32 v137, 0xffff0000, v134
	s_waitcnt vmcnt(58)
	v_lshlrev_b32_e32 v138, 16, v132
	v_and_b32_e32 v139, 0xffff0000, v132
	v_lshlrev_b32_e32 v134, 16, v135
	v_and_b32_e32 v135, 0xffff0000, v135
	v_lshlrev_b32_e32 v132, 16, v133
	v_and_b32_e32 v133, 0xffff0000, v133
	v_pk_fma_f32 v[136:137], v[136:137], s[78:79], v[138:139] op_sel_hi:[1,0,1]
	v_pk_fma_f32 v[132:133], v[134:135], s[78:79], v[132:133] op_sel_hi:[1,0,1]
	s_waitcnt vmcnt(57)
	v_lshlrev_b32_e32 v134, 16, v130
	v_and_b32_e32 v135, 0xffff0000, v130
	s_waitcnt vmcnt(56)
	v_lshlrev_b32_e32 v138, 16, v128
	v_and_b32_e32 v139, 0xffff0000, v128
	v_lshlrev_b32_e32 v130, 16, v131
	v_and_b32_e32 v131, 0xffff0000, v131
	v_lshlrev_b32_e32 v128, 16, v129
	v_and_b32_e32 v129, 0xffff0000, v129
	v_pk_fma_f32 v[134:135], v[134:135], s[78:79], v[138:139] op_sel_hi:[1,0,1]
	v_pk_fma_f32 v[128:129], v[130:131], s[78:79], v[128:129] op_sel_hi:[1,0,1]
	s_waitcnt vmcnt(55)
	v_lshlrev_b32_e32 v130, 16, v126
	v_and_b32_e32 v131, 0xffff0000, v126
	s_waitcnt vmcnt(54)
	v_lshlrev_b32_e32 v138, 16, v124
	v_and_b32_e32 v139, 0xffff0000, v124
	v_lshlrev_b32_e32 v126, 16, v127
	v_and_b32_e32 v127, 0xffff0000, v127
	v_lshlrev_b32_e32 v124, 16, v125
	v_and_b32_e32 v125, 0xffff0000, v125
	v_pk_fma_f32 v[130:131], v[130:131], s[78:79], v[138:139] op_sel_hi:[1,0,1]
	v_pk_fma_f32 v[138:139], v[126:127], s[78:79], v[124:125] op_sel_hi:[1,0,1]
	s_waitcnt vmcnt(53)
	v_lshlrev_b32_e32 v124, 16, v120
	v_and_b32_e32 v125, 0xffff0000, v120
	s_waitcnt vmcnt(52)
	v_lshlrev_b32_e32 v126, 16, v122
	v_and_b32_e32 v127, 0xffff0000, v122
	v_lshlrev_b32_e32 v120, 16, v121
	v_and_b32_e32 v121, 0xffff0000, v121
	v_lshlrev_b32_e32 v122, 16, v123
	v_and_b32_e32 v123, 0xffff0000, v123
	v_pk_fma_f32 v[142:143], v[120:121], s[78:79], v[122:123] op_sel_hi:[1,0,1]
	v_mov_b32_e32 v120, v136
	v_mov_b32_e32 v121, v132
	v_mov_b32_e32 v122, v137
	v_mov_b32_e32 v123, v133
	v_pk_fma_f32 v[140:141], v[124:125], s[78:79], v[126:127] op_sel_hi:[1,0,1]
	v_pk_add_f32 v[120:121], v[120:121], v[122:123]
	v_mov_b32_e32 v122, v134
	v_mov_b32_e32 v123, v128
	v_mov_b32_e32 v124, v135
	v_mov_b32_e32 v125, v129
	v_pk_add_f32 v[122:123], v[122:123], v[124:125]
	v_add_f32_e32 v9, v120, v121
	v_pk_add_f32 v[122:123], v[122:123], v[122:123] op_sel:[0,1] op_sel_hi:[1,0]
	v_pk_add_f32 v[124:125], v[130:131], v[130:131] op_sel:[0,1] op_sel_hi:[1,0]
	v_pk_add_f32 v[126:127], v[138:139], v[138:139] op_sel:[0,1] op_sel_hi:[1,0]
	v_add_f32_e32 v120, 0, v9
	v_mov_b32_e32 v121, v140
	v_mov_b32_e32 v123, v141
	v_mov_b32_e32 v125, v142
	v_mov_b32_e32 v127, v143
	v_pk_add_f32 v[120:121], v[120:121], v[122:123]
	v_pk_add_f32 v[122:123], v[124:125], v[126:127]
	s_nop 0
	v_pk_add_f32 v[120:121], v[120:121], v[122:123]
	s_nop 0
	v_add_f32_e32 v9, v120, v121
	s_waitcnt lgkmcnt(0)
	s_nop 1
	v_add_f32_dpp v9, v9, v9 quad_perm:[1,0,3,2] row_mask:0xf bank_mask:0xf
	s_waitcnt lgkmcnt(0)
	s_nop 1
	v_add_f32_dpp v9, v9, v9 quad_perm:[2,3,0,1] row_mask:0xf bank_mask:0xf
	s_waitcnt lgkmcnt(0)
	s_nop 1
	v_add_f32_dpp v9, v9, v9 row_half_mirror row_mask:0xf bank_mask:0xf
	s_waitcnt lgkmcnt(0)
	s_nop 1
	v_add_f32_dpp v9, v9, v9 row_mirror row_mask:0xf bank_mask:0xf
	s_waitcnt lgkmcnt(0)
	v_mov_b32_e32 v120, v9
	s_nop 1
	v_permlane16_swap_b32 v9, v120
	v_add_f32_e32 v9, v9, v120
	s_waitcnt lgkmcnt(0)
; #define LAS __attribute__((address_space(3)))
; __device__ __forceinline__ float bf_lo(unsigned u) { return __uint_as_float(u << 16); }
; __device__ __forceinline__ float bf_hi(unsigned u) { return __uint_as_float(u & 0xffff0000u); }
; __device__ __forceinline__ void ln_affine_l(f32x4 (&v)[4], const LAS float* gL, const LAS float* bL, int lane) {
;     float s = 0.f;
; #pragma unroll
;     for (int j = 0; j < 4; ++j) s += (v[j].x + v[j].y) + (v[j].z + v[j].w);
;     const float mean = wave_sum(s) * (1.f / D_); float s2 = 0.f;
; #pragma unroll
;     for (int j = 0; j < 4; ++j) { v[j] = v[j] - mean; s2 += (v[j].x * v[j].x + v[j].y * v[j].y) + (v[j].z * v[j].z + v[j].w * v[j].w); }
;     const float rstd = 1.f / sqrtf(wave_sum(s2) * (1.f / D_) + LN_EPS_);
; #pragma unroll
;     for (int j = 0; j < 4; ++j) v[j] = v[j] * rstd * *(const LAS f32x4*)(gL + 4 * lane + 256 * j) + *(const LAS f32x4*)(bL + 4 * lane + 256 * j);
; }
; __device__ __forceinline__ void ln1_router_tile(KArgs A, int l, int tile, int lane, const LAS bf16_t* wH) {
;     ...
;         for (int i = 0; i < 8; ++i) { f32x4 hv[4];
; #pragma unroll
;             for (int j = 0; j < 4; ++j) { hv[j].x = bf_lo(hr[i][j].x) * ALPHA_ + bf_lo(mm[i][j].x); hv[j].y = bf_hi(hr[i][j].x) * ALPHA_ + bf_hi(mm[i][j].x); hv[j].z = bf_lo(hr[i][j].y) * ALPHA_ + bf_lo(mm[i][j].y); hv[j].w = bf_hi(hr[i][j].y) * ALPHA_ + bf_hi(mm[i][j].y); }
;             ln_affine_l(hv, gL, bL, lane); store_row_bf16(HB + (size_t)(r0 + i) * D_, hv, lane); }
	v_mov_b32_e32 v120, v9
	s_nop 1
	v_permlane32_swap_b32 v9, v120
	v_add_f32_e32 v9, v9, v120
	v_fmamk_f32 v137, v9, 0xba800000, v137
	v_fmac_f32_e32 v136, 0xba800000, v9
	v_fmamk_f32 v133, v9, 0xba800000, v133
	v_fmac_f32_e32 v132, 0xba800000, v9
	v_pk_mul_f32 v[120:121], v[132:133], v[132:133]
	v_pk_mul_f32 v[122:123], v[136:137], v[136:137]
	v_fmamk_f32 v135, v9, 0xba800000, v135
	v_pk_mov_b32 v[124:125], v[122:123], v[120:121] op_sel:[1,0]
	v_mov_b32_e32 v123, v121
	v_pk_add_f32 v[120:121], v[124:125], v[122:123]
	v_fmac_f32_e32 v134, 0xba800000, v9
	v_fmamk_f32 v129, v9, 0xba800000, v129
	v_fmac_f32_e32 v128, 0xba800000, v9
	v_pk_add_f32 v[120:121], v[120:121], v[120:121] op_sel_hi:[0,1]
	v_pk_mul_f32 v[122:123], v[128:129], v[128:129]
	v_pk_mul_f32 v[124:125], v[134:135], v[134:135]
	v_fmac_f32_e32 v130, 0xba800000, v9
	v_pk_mov_b32 v[126:127], v[124:125], v[122:123] op_sel:[1,0]
	v_mov_b32_e32 v125, v123
	v_fmamk_f32 v131, v9, 0xba800000, v131
	v_fmac_f32_e32 v138, 0xba800000, v9
	v_mul_f32_e32 v120, v130, v130
	v_pk_add_f32 v[122:123], v[126:127], v[124:125]
	v_fmamk_f32 v139, v9, 0xba800000, v139
	v_pk_fma_f32 v[124:125], v[130:131], v[130:131], v[120:121] op_sel_hi:[1,1,0]
	v_mul_f32_e32 v120, v138, v138
	v_pk_add_f32 v[122:123], v[122:123], v[122:123] op_sel_hi:[0,1]
	v_pk_fma_f32 v[126:127], v[138:139], v[138:139], v[120:121] op_sel_hi:[1,1,0]
	v_fmamk_f32 v143, v9, 0xba800000, v143
	v_fmac_f32_e32 v142, 0xba800000, v9
	v_fmamk_f32 v141, v9, 0xba800000, v141
	v_fmac_f32_e32 v140, 0xba800000, v9
	v_mul_f32_e32 v124, v140, v140
	v_mul_f32_e32 v126, v141, v141
	v_mul_f32_e32 v120, v142, v142
	v_mul_f32_e32 v122, v143, v143
	v_pk_add_f32 v[124:125], v[124:125], v[126:127]
	v_pk_add_f32 v[120:121], v[120:121], v[122:123]
	s_nop 0
	v_pk_add_f32 v[120:121], v[124:125], v[120:121]
	s_nop 0
	v_add_f32_e32 v9, v120, v121
	s_waitcnt lgkmcnt(0)
	s_nop 1
	v_add_f32_dpp v9, v9, v9 quad_perm:[1,0,3,2] row_mask:0xf bank_mask:0xf
	s_waitcnt lgkmcnt(0)
	s_nop 1
	v_add_f32_dpp v9, v9, v9 quad_perm:[2,3,0,1] row_mask:0xf bank_mask:0xf
	s_waitcnt lgkmcnt(0)
	s_nop 1
	v_add_f32_dpp v9, v9, v9 row_half_mirror row_mask:0xf bank_mask:0xf
	s_waitcnt lgkmcnt(0)
	s_nop 1
	v_add_f32_dpp v9, v9, v9 row_mirror row_mask:0xf bank_mask:0xf
	s_waitcnt lgkmcnt(0)
	v_mov_b32_e32 v120, v9
	s_nop 1
	v_permlane16_swap_b32 v9, v120
	v_add_f32_e32 v9, v9, v120
	s_waitcnt lgkmcnt(0)
	v_mov_b32_e32 v120, v9
	s_nop 1
	v_permlane32_swap_b32 v9, v120
	v_add_f32_e32 v9, v9, v120
	v_fmamk_f32 v9, v9, 0x3a800000, v227
	v_cmp_gt_f32_e32 vcc, s47, v9
	v_mul_f32_e32 v120, 0x4f800000, v9
	s_nop 0
	v_cndmask_b32_e32 v9, v9, v120, vcc
	v_sqrt_f32_e32 v120, v9
	s_nop 0
	v_add_u32_e32 v121, -1, v120
	v_fma_f32 v122, -v121, v120, v9
	v_cmp_ge_f32_e64 s[8:9], 0, v122
	v_add_u32_e32 v122, 1, v120
	s_nop 0
	v_cndmask_b32_e64 v121, v120, v121, s[8:9]
	v_fma_f32 v120, -v122, v120, v9
	v_cmp_lt_f32_e64 s[8:9], 0, v120
	s_nop 1
	v_cndmask_b32_e64 v120, v121, v122, s[8:9]
	v_mul_f32_e32 v121, 0x37800000, v120
	v_cndmask_b32_e32 v120, v120, v121, vcc
	v_cmp_class_f32_e32 vcc, v9, v228
	s_nop 1
	v_cndmask_b32_e32 v9, v120, v9, vcc
	v_div_scale_f32 v120, s[0:1], v9, v9, 1.0
	v_rcp_f32_e32 v121, v120
	s_nop 0
	v_fma_f32 v122, -v120, v121, 1.0
	v_fmac_f32_e32 v121, v122, v121
	v_div_scale_f32 v122, vcc, 1.0, v9, 1.0
	v_mul_f32_e32 v123, v122, v121
	v_fma_f32 v124, -v120, v123, v122
	v_fmac_f32_e32 v123, v124, v121
	v_fma_f32 v120, -v120, v123, v122
	v_div_fmas_f32 v120, v120, v121, v123
	v_div_fixup_f32 v144, v120, v9, 1.0
	ds_read_b128 v[120:123], v152
	ds_read_b128 v[124:127], v153
	v_pk_mul_f32 v[136:137], v[136:137], v[144:145] op_sel_hi:[1,0]
	v_pk_mul_f32 v[132:133], v[132:133], v[144:145] op_sel_hi:[1,0]
	v_pk_mul_f32 v[134:135], v[134:135], v[144:145] op_sel_hi:[1,0]
	v_pk_mul_f32 v[128:129], v[128:129], v[144:145] op_sel_hi:[1,0]
	s_waitcnt lgkmcnt(0)
	v_pk_fma_f32 v[132:133], v[122:123], v[132:133], v[126:127]
	v_pk_fma_f32 v[136:137], v[120:121], v[136:137], v[124:125]
	ds_read_b128 v[120:123], v152 offset:1024
	ds_read_b128 v[124:127], v153 offset:1024
	v_pk_mul_f32 v[130:131], v[130:131], v[144:145] op_sel_hi:[1,0]
	v_pk_mul_f32 v[138:139], v[138:139], v[144:145] op_sel_hi:[1,0]
	v_pk_mul_f32 v[140:141], v[140:141], v[144:145] op_sel_hi:[1,0]
	v_pk_mul_f32 v[142:143], v[142:143], v[144:145] op_sel_hi:[1,0]
	s_waitcnt lgkmcnt(0)
	v_pk_fma_f32 v[128:129], v[122:123], v[128:129], v[126:127]
	v_pk_fma_f32 v[134:135], v[120:121], v[134:135], v[124:125]
	ds_read_b128 v[120:123], v152 offset:2048
	ds_read_b128 v[124:127], v153 offset:2048
	s_waitcnt lgkmcnt(0)
	v_pk_fma_f32 v[138:139], v[122:123], v[138:139], v[126:127]
	v_pk_fma_f32 v[130:131], v[120:121], v[130:131], v[124:125]
	ds_read_b128 v[120:123], v152 offset:3072
	ds_read_b128 v[124:127], v153 offset:3072
	s_waitcnt lgkmcnt(0)
	v_pk_fma_f32 v[120:121], v[120:121], v[140:141], v[124:125]
	v_cvt_pk_bf16_f32 v124, v136, v137
	v_cvt_pk_bf16_f32 v125, v132, v133
	global_store_dwordx2 v[118:119], v[124:125], off offset:2048
	v_cvt_pk_bf16_f32 v124, v134, v135
	v_cvt_pk_bf16_f32 v125, v128, v129
	v_pk_fma_f32 v[122:123], v[122:123], v[142:143], v[126:127]
	global_store_dwordx2 v[118:119], v[124:125], off offset:2560
	v_cvt_pk_bf16_f32 v124, v130, v131
	v_cvt_pk_bf16_f32 v125, v138, v139
	global_store_dwordx2 v[118:119], v[124:125], off offset:3072
	v_cvt_pk_bf16_f32 v120, v120, v121
	v_cvt_pk_bf16_f32 v121, v122, v123
	global_store_dwordx2 v[118:119], v[120:121], off offset:3584
	s_waitcnt vmcnt(55)
	v_lshlrev_b32_e32 v118, 16, v116
	v_and_b32_e32 v119, 0xffff0000, v116
	s_waitcnt vmcnt(54)
; #define LAS __attribute__((address_space(3)))
; __device__ __forceinline__ float bf_lo(unsigned u) { return __uint_as_float(u << 16); }
; __device__ __forceinline__ float bf_hi(unsigned u) { return __uint_as_float(u & 0xffff0000u); }
; __device__ __forceinline__ void ln_affine_l(f32x4 (&v)[4], const LAS float* gL, const LAS float* bL, int lane) {
;     float s = 0.f;
; #pragma unroll
;     for (int j = 0; j < 4; ++j) s += (v[j].x + v[j].y) + (v[j].z + v[j].w);
;     const float mean = wave_sum(s) * (1.f / D_); float s2 = 0.f;
; #pragma unroll
;     for (int j = 0; j < 4; ++j) { v[j] = v[j] - mean; s2 += (v[j].x * v[j].x + v[j].y * v[j].y) + (v[j].z * v[j].z + v[j].w * v[j].w); }
;     const float rstd = 1.f / sqrtf(wave_sum(s2) * (1.f / D_) + LN_EPS_);
; #pragma unroll
;     for (int j = 0; j < 4; ++j) v[j] = v[j] * rstd * *(const LAS f32x4*)(gL + 4 * lane + 256 * j) + *(const LAS f32x4*)(bL + 4 * lane + 256 * j);
; }
; __device__ __forceinline__ void ln1_router_tile(KArgs A, int l, int tile, int lane, const LAS bf16_t* wH) {
;     ...
;         for (int i = 0; i < 8; ++i) { f32x4 hv[4];
; #pragma unroll
;             for (int j = 0; j < 4; ++j) { hv[j].x = bf_lo(hr[i][j].x) * ALPHA_ + bf_lo(mm[i][j].x); hv[j].y = bf_hi(hr[i][j].x) * ALPHA_ + bf_hi(mm[i][j].x); hv[j].z = bf_lo(hr[i][j].y) * ALPHA_ + bf_lo(mm[i][j].y); hv[j].w = bf_hi(hr[i][j].y) * ALPHA_ + bf_hi(mm[i][j].y); }
;             ln_affine_l(hv, gL, bL, lane); store_row_bf16(HB + (size_t)(r0 + i) * D_, hv, lane); }
	v_lshlrev_b32_e32 v120, 16, v114
	v_and_b32_e32 v121, 0xffff0000, v114
	v_lshlrev_b32_e32 v116, 16, v117
	v_and_b32_e32 v117, 0xffff0000, v117
	v_lshlrev_b32_e32 v114, 16, v115
	v_and_b32_e32 v115, 0xffff0000, v115
	v_pk_fma_f32 v[118:119], v[118:119], s[78:79], v[120:121] op_sel_hi:[1,0,1]
	v_pk_fma_f32 v[114:115], v[116:117], s[78:79], v[114:115] op_sel_hi:[1,0,1]
	s_waitcnt vmcnt(53)
	v_lshlrev_b32_e32 v116, 16, v112
	v_and_b32_e32 v117, 0xffff0000, v112
	s_waitcnt vmcnt(52)
	v_lshlrev_b32_e32 v120, 16, v110
	v_and_b32_e32 v121, 0xffff0000, v110
	v_lshlrev_b32_e32 v112, 16, v113
	v_and_b32_e32 v113, 0xffff0000, v113
	v_lshlrev_b32_e32 v110, 16, v111
	v_and_b32_e32 v111, 0xffff0000, v111
	v_pk_fma_f32 v[116:117], v[116:117], s[78:79], v[120:121] op_sel_hi:[1,0,1]
	v_pk_fma_f32 v[110:111], v[112:113], s[78:79], v[110:111] op_sel_hi:[1,0,1]
	s_waitcnt vmcnt(51)
	v_lshlrev_b32_e32 v112, 16, v108
	v_and_b32_e32 v113, 0xffff0000, v108
	s_waitcnt vmcnt(50)
	v_lshlrev_b32_e32 v120, 16, v106
	v_and_b32_e32 v121, 0xffff0000, v106
	v_lshlrev_b32_e32 v108, 16, v109
	v_and_b32_e32 v109, 0xffff0000, v109
	v_lshlrev_b32_e32 v106, 16, v107
	v_and_b32_e32 v107, 0xffff0000, v107
	v_pk_fma_f32 v[112:113], v[112:113], s[78:79], v[120:121] op_sel_hi:[1,0,1]
	v_pk_fma_f32 v[120:121], v[108:109], s[78:79], v[106:107] op_sel_hi:[1,0,1]
	s_waitcnt vmcnt(49)
	v_lshlrev_b32_e32 v106, 16, v104
	v_and_b32_e32 v107, 0xffff0000, v104
	s_waitcnt vmcnt(48)
	v_lshlrev_b32_e32 v108, 16, v102
	v_and_b32_e32 v109, 0xffff0000, v102
	v_lshlrev_b32_e32 v104, 16, v105
	v_and_b32_e32 v105, 0xffff0000, v105
	v_lshlrev_b32_e32 v102, 16, v103
	v_and_b32_e32 v103, 0xffff0000, v103
	v_pk_fma_f32 v[124:125], v[104:105], s[78:79], v[102:103] op_sel_hi:[1,0,1]
	v_mov_b32_e32 v102, v118
	v_mov_b32_e32 v103, v114
	v_mov_b32_e32 v104, v119
	v_mov_b32_e32 v105, v115
	v_pk_fma_f32 v[122:123], v[106:107], s[78:79], v[108:109] op_sel_hi:[1,0,1]
	v_pk_add_f32 v[102:103], v[102:103], v[104:105]
	v_mov_b32_e32 v104, v116
	v_mov_b32_e32 v105, v110
	v_mov_b32_e32 v106, v117
	v_mov_b32_e32 v107, v111
	v_pk_add_f32 v[104:105], v[104:105], v[106:107]
	v_add_f32_e32 v9, v102, v103
	v_pk_add_f32 v[104:105], v[104:105], v[104:105] op_sel:[0,1] op_sel_hi:[1,0]
	v_pk_add_f32 v[106:107], v[112:113], v[112:113] op_sel:[0,1] op_sel_hi:[1,0]
	v_pk_add_f32 v[108:109], v[120:121], v[120:121] op_sel:[0,1] op_sel_hi:[1,0]
	v_add_f32_e32 v102, 0, v9
	v_mov_b32_e32 v103, v122
	v_mov_b32_e32 v105, v123
	v_mov_b32_e32 v107, v124
	v_mov_b32_e32 v109, v125
	v_pk_add_f32 v[102:103], v[102:103], v[104:105]
	v_pk_add_f32 v[104:105], v[106:107], v[108:109]
	s_nop 0
	v_pk_add_f32 v[102:103], v[102:103], v[104:105]
	s_nop 0
	v_add_f32_e32 v9, v102, v103
	s_waitcnt lgkmcnt(0)
	s_nop 1
	v_add_f32_dpp v9, v9, v9 quad_perm:[1,0,3,2] row_mask:0xf bank_mask:0xf
	s_waitcnt lgkmcnt(0)
	s_nop 1
	v_add_f32_dpp v9, v9, v9 quad_perm:[2,3,0,1] row_mask:0xf bank_mask:0xf
	s_waitcnt lgkmcnt(0)
	s_nop 1
	v_add_f32_dpp v9, v9, v9 row_half_mirror row_mask:0xf bank_mask:0xf
	s_waitcnt lgkmcnt(0)
	s_nop 1
	v_add_f32_dpp v9, v9, v9 row_mirror row_mask:0xf bank_mask:0xf
	s_waitcnt lgkmcnt(0)
	v_mov_b32_e32 v102, v9
	s_nop 1
	v_permlane16_swap_b32 v9, v102
	v_add_f32_e32 v9, v9, v102
	s_waitcnt lgkmcnt(0)
	v_mov_b32_e32 v102, v9
	s_nop 1
	v_permlane32_swap_b32 v9, v102
	v_add_f32_e32 v9, v9, v102
	v_fmamk_f32 v119, v9, 0xba800000, v119
	v_fmac_f32_e32 v118, 0xba800000, v9
	v_fmamk_f32 v115, v9, 0xba800000, v115
	v_fmac_f32_e32 v114, 0xba800000, v9
	v_pk_mul_f32 v[102:103], v[114:115], v[114:115]
	v_pk_mul_f32 v[104:105], v[118:119], v[118:119]
	v_fmamk_f32 v117, v9, 0xba800000, v117
	v_pk_mov_b32 v[106:107], v[104:105], v[102:103] op_sel:[1,0]
	v_mov_b32_e32 v105, v103
	v_pk_add_f32 v[102:103], v[106:107], v[104:105]
	v_fmac_f32_e32 v116, 0xba800000, v9
	v_fmamk_f32 v111, v9, 0xba800000, v111
	v_fmac_f32_e32 v110, 0xba800000, v9
	v_pk_add_f32 v[102:103], v[102:103], v[102:103] op_sel_hi:[0,1]
	v_pk_mul_f32 v[104:105], v[110:111], v[110:111]
	v_pk_mul_f32 v[106:107], v[116:117], v[116:117]
	v_fmac_f32_e32 v112, 0xba800000, v9
	v_pk_mov_b32 v[108:109], v[106:107], v[104:105] op_sel:[1,0]
	v_mov_b32_e32 v107, v105
	v_fmamk_f32 v113, v9, 0xba800000, v113
	v_fmac_f32_e32 v120, 0xba800000, v9
	v_mul_f32_e32 v102, v112, v112
	v_pk_add_f32 v[104:105], v[108:109], v[106:107]
	v_fmamk_f32 v121, v9, 0xba800000, v121
	v_pk_fma_f32 v[106:107], v[112:113], v[112:113], v[102:103] op_sel_hi:[1,1,0]
	v_mul_f32_e32 v102, v120, v120
	v_pk_add_f32 v[104:105], v[104:105], v[104:105] op_sel_hi:[0,1]
	v_pk_fma_f32 v[108:109], v[120:121], v[120:121], v[102:103] op_sel_hi:[1,1,0]
	v_fmamk_f32 v125, v9, 0xba800000, v125
	v_fmac_f32_e32 v124, 0xba800000, v9
	v_fmamk_f32 v123, v9, 0xba800000, v123
	v_fmac_f32_e32 v122, 0xba800000, v9
	v_mul_f32_e32 v106, v122, v122
	v_mul_f32_e32 v108, v123, v123
	v_mul_f32_e32 v102, v124, v124
	v_mul_f32_e32 v104, v125, v125
	v_pk_add_f32 v[106:107], v[106:107], v[108:109]
	v_pk_add_f32 v[102:103], v[102:103], v[104:105]
	s_nop 0
	v_pk_add_f32 v[102:103], v[106:107], v[102:103]
	s_nop 0
	v_add_f32_e32 v9, v102, v103
	s_waitcnt lgkmcnt(0)
	s_nop 1
	v_add_f32_dpp v9, v9, v9 quad_perm:[1,0,3,2] row_mask:0xf bank_mask:0xf
	s_waitcnt lgkmcnt(0)
	s_nop 1
	v_add_f32_dpp v9, v9, v9 quad_perm:[2,3,0,1] row_mask:0xf bank_mask:0xf
	s_waitcnt lgkmcnt(0)
	s_nop 1
	v_add_f32_dpp v9, v9, v9 row_half_mirror row_mask:0xf bank_mask:0xf
	s_waitcnt lgkmcnt(0)
	s_nop 1
	v_add_f32_dpp v9, v9, v9 row_mirror row_mask:0xf bank_mask:0xf
	s_waitcnt lgkmcnt(0)
	v_mov_b32_e32 v102, v9
	s_nop 1
	v_permlane16_swap_b32 v9, v102
	v_add_f32_e32 v9, v9, v102
	s_waitcnt lgkmcnt(0)
; #define LAS __attribute__((address_space(3)))
; __device__ __forceinline__ float bf_lo(unsigned u) { return __uint_as_float(u << 16); }
; __device__ __forceinline__ float bf_hi(unsigned u) { return __uint_as_float(u & 0xffff0000u); }
; __device__ __forceinline__ void ln_affine_l(f32x4 (&v)[4], const LAS float* gL, const LAS float* bL, int lane) {
;     float s = 0.f;
; #pragma unroll
;     for (int j = 0; j < 4; ++j) s += (v[j].x + v[j].y) + (v[j].z + v[j].w);
;     const float mean = wave_sum(s) * (1.f / D_); float s2 = 0.f;
; #pragma unroll
;     for (int j = 0; j < 4; ++j) { v[j] = v[j] - mean; s2 += (v[j].x * v[j].x + v[j].y * v[j].y) + (v[j].z * v[j].z + v[j].w * v[j].w); }
;     const float rstd = 1.f / sqrtf(wave_sum(s2) * (1.f / D_) + LN_EPS_);
; #pragma unroll
;     for (int j = 0; j < 4; ++j) v[j] = v[j] * rstd * *(const LAS f32x4*)(gL + 4 * lane + 256 * j) + *(const LAS f32x4*)(bL + 4 * lane + 256 * j);
; }
; __device__ __forceinline__ void ln1_router_tile(KArgs A, int l, int tile, int lane, const LAS bf16_t* wH) {
;     ...
;         for (int i = 0; i < 8; ++i) { f32x4 hv[4];
; #pragma unroll
;             for (int j = 0; j < 4; ++j) { hv[j].x = bf_lo(hr[i][j].x) * ALPHA_ + bf_lo(mm[i][j].x); hv[j].y = bf_hi(hr[i][j].x) * ALPHA_ + bf_hi(mm[i][j].x); hv[j].z = bf_lo(hr[i][j].y) * ALPHA_ + bf_lo(mm[i][j].y); hv[j].w = bf_hi(hr[i][j].y) * ALPHA_ + bf_hi(mm[i][j].y); }
;             ln_affine_l(hv, gL, bL, lane); store_row_bf16(HB + (size_t)(r0 + i) * D_, hv, lane); }
	v_mov_b32_e32 v102, v9
	s_nop 1
	v_permlane32_swap_b32 v9, v102
	v_add_f32_e32 v9, v9, v102
	v_fmamk_f32 v9, v9, 0x3a800000, v227
	v_cmp_gt_f32_e32 vcc, s47, v9
	v_mul_f32_e32 v102, 0x4f800000, v9
	s_nop 0
	v_cndmask_b32_e32 v9, v9, v102, vcc
	v_sqrt_f32_e32 v102, v9
	s_nop 0
	v_add_u32_e32 v103, -1, v102
	v_fma_f32 v104, -v103, v102, v9
	v_cmp_ge_f32_e64 s[8:9], 0, v104
	v_add_u32_e32 v104, 1, v102
	s_nop 0
	v_cndmask_b32_e64 v103, v102, v103, s[8:9]
	v_fma_f32 v102, -v104, v102, v9
	v_cmp_lt_f32_e64 s[8:9], 0, v102
	s_nop 1
	v_cndmask_b32_e64 v102, v103, v104, s[8:9]
	v_mul_f32_e32 v103, 0x37800000, v102
	v_cndmask_b32_e32 v102, v102, v103, vcc
	v_cmp_class_f32_e32 vcc, v9, v228
	s_nop 1
	v_cndmask_b32_e32 v9, v102, v9, vcc
	v_div_scale_f32 v102, s[0:1], v9, v9, 1.0
	v_rcp_f32_e32 v103, v102
	s_nop 0
	v_fma_f32 v104, -v102, v103, 1.0
	v_fmac_f32_e32 v103, v104, v103
	v_div_scale_f32 v104, vcc, 1.0, v9, 1.0
	v_mul_f32_e32 v105, v104, v103
	v_fma_f32 v106, -v102, v105, v104
	v_fmac_f32_e32 v105, v106, v103
	v_fma_f32 v102, -v102, v105, v104
	v_div_fmas_f32 v102, v102, v103, v105
	v_div_fixup_f32 v126, v102, v9, 1.0
	ds_read_b128 v[102:105], v152
	ds_read_b128 v[106:109], v153
	v_pk_mul_f32 v[118:119], v[118:119], v[126:127] op_sel_hi:[1,0]
	v_pk_mul_f32 v[114:115], v[114:115], v[126:127] op_sel_hi:[1,0]
	v_pk_mul_f32 v[116:117], v[116:117], v[126:127] op_sel_hi:[1,0]
	v_pk_mul_f32 v[110:111], v[110:111], v[126:127] op_sel_hi:[1,0]
	s_waitcnt lgkmcnt(0)
	v_pk_fma_f32 v[114:115], v[104:105], v[114:115], v[108:109]
	v_pk_fma_f32 v[118:119], v[102:103], v[118:119], v[106:107]
	ds_read_b128 v[102:105], v152 offset:1024
	ds_read_b128 v[106:109], v153 offset:1024
	v_pk_mul_f32 v[112:113], v[112:113], v[126:127] op_sel_hi:[1,0]
	v_pk_mul_f32 v[120:121], v[120:121], v[126:127] op_sel_hi:[1,0]
	v_pk_mul_f32 v[122:123], v[122:123], v[126:127] op_sel_hi:[1,0]
	v_pk_mul_f32 v[124:125], v[124:125], v[126:127] op_sel_hi:[1,0]
	s_waitcnt lgkmcnt(0)
	v_pk_fma_f32 v[110:111], v[104:105], v[110:111], v[108:109]
	v_pk_fma_f32 v[116:117], v[102:103], v[116:117], v[106:107]
	ds_read_b128 v[102:105], v152 offset:2048
	ds_read_b128 v[106:109], v153 offset:2048
	s_waitcnt lgkmcnt(0)
	v_pk_fma_f32 v[120:121], v[104:105], v[120:121], v[108:109]
	v_pk_fma_f32 v[112:113], v[102:103], v[112:113], v[106:107]
	ds_read_b128 v[102:105], v152 offset:3072
	ds_read_b128 v[106:109], v153 offset:3072
	s_waitcnt lgkmcnt(0)
	v_pk_fma_f32 v[102:103], v[102:103], v[122:123], v[106:107]
	v_cvt_pk_bf16_f32 v106, v118, v119
	v_cvt_pk_bf16_f32 v107, v114, v115
	global_store_dwordx2 v[100:101], v[106:107], off
	v_cvt_pk_bf16_f32 v106, v116, v117
	v_cvt_pk_bf16_f32 v107, v110, v111
	v_pk_fma_f32 v[104:105], v[104:105], v[124:125], v[108:109]
	global_store_dwordx2 v[100:101], v[106:107], off offset:512
	v_cvt_pk_bf16_f32 v106, v112, v113
	v_cvt_pk_bf16_f32 v107, v120, v121
	global_store_dwordx2 v[100:101], v[106:107], off offset:1024
	v_cvt_pk_bf16_f32 v102, v102, v103
	v_cvt_pk_bf16_f32 v103, v104, v105
	global_store_dwordx2 v[100:101], v[102:103], off offset:1536
	s_waitcnt vmcnt(51)
	v_lshlrev_b32_e32 v100, 16, v98
	v_and_b32_e32 v101, 0xffff0000, v98
	s_waitcnt vmcnt(50)
	v_lshlrev_b32_e32 v102, 16, v96
	v_and_b32_e32 v103, 0xffff0000, v96
	v_lshlrev_b32_e32 v98, 16, v99
	v_and_b32_e32 v99, 0xffff0000, v99
	v_lshlrev_b32_e32 v96, 16, v97
	v_and_b32_e32 v97, 0xffff0000, v97
	v_pk_fma_f32 v[100:101], v[100:101], s[78:79], v[102:103] op_sel_hi:[1,0,1]
	v_pk_fma_f32 v[96:97], v[98:99], s[78:79], v[96:97] op_sel_hi:[1,0,1]
	s_waitcnt vmcnt(49)
	v_lshlrev_b32_e32 v98, 16, v94
	v_and_b32_e32 v99, 0xffff0000, v94
	s_waitcnt vmcnt(48)
	v_lshlrev_b32_e32 v102, 16, v92
	v_and_b32_e32 v103, 0xffff0000, v92
	v_lshlrev_b32_e32 v94, 16, v95
	v_and_b32_e32 v95, 0xffff0000, v95
	v_lshlrev_b32_e32 v92, 16, v93
	v_and_b32_e32 v93, 0xffff0000, v93
	v_pk_fma_f32 v[98:99], v[98:99], s[78:79], v[102:103] op_sel_hi:[1,0,1]
	v_pk_fma_f32 v[92:93], v[94:95], s[78:79], v[92:93] op_sel_hi:[1,0,1]
	s_waitcnt vmcnt(47)
	v_lshlrev_b32_e32 v94, 16, v90
	v_and_b32_e32 v95, 0xffff0000, v90
	s_waitcnt vmcnt(46)
	v_lshlrev_b32_e32 v102, 16, v88
	v_and_b32_e32 v103, 0xffff0000, v88
	v_lshlrev_b32_e32 v90, 16, v91
	v_and_b32_e32 v91, 0xffff0000, v91
	v_lshlrev_b32_e32 v88, 16, v89
	v_and_b32_e32 v89, 0xffff0000, v89
	v_pk_fma_f32 v[94:95], v[94:95], s[78:79], v[102:103] op_sel_hi:[1,0,1]
	v_pk_fma_f32 v[102:103], v[90:91], s[78:79], v[88:89] op_sel_hi:[1,0,1]
	s_waitcnt vmcnt(45)
	v_lshlrev_b32_e32 v88, 16, v86
	v_and_b32_e32 v89, 0xffff0000, v86
	s_waitcnt vmcnt(44)
	v_lshlrev_b32_e32 v90, 16, v84
	v_and_b32_e32 v91, 0xffff0000, v84
	v_lshlrev_b32_e32 v86, 16, v87
	v_and_b32_e32 v87, 0xffff0000, v87
	v_lshlrev_b32_e32 v84, 16, v85
	v_and_b32_e32 v85, 0xffff0000, v85
	v_pk_fma_f32 v[106:107], v[86:87], s[78:79], v[84:85] op_sel_hi:[1,0,1]
	v_mov_b32_e32 v84, v100
	v_mov_b32_e32 v85, v96
	v_mov_b32_e32 v86, v101
	v_mov_b32_e32 v87, v97
	v_pk_fma_f32 v[104:105], v[88:89], s[78:79], v[90:91] op_sel_hi:[1,0,1]
	v_pk_add_f32 v[84:85], v[84:85], v[86:87]
	v_mov_b32_e32 v86, v98
	v_mov_b32_e32 v87, v92
	v_mov_b32_e32 v88, v99
	v_mov_b32_e32 v89, v93
	v_pk_add_f32 v[86:87], v[86:87], v[88:89]
	v_add_f32_e32 v9, v84, v85
	v_pk_add_f32 v[86:87], v[86:87], v[86:87] op_sel:[0,1] op_sel_hi:[1,0]
	v_pk_add_f32 v[88:89], v[94:95], v[94:95] op_sel:[0,1] op_sel_hi:[1,0]
	v_pk_add_f32 v[90:91], v[102:103], v[102:103] op_sel:[0,1] op_sel_hi:[1,0]
	v_add_f32_e32 v84, 0, v9
	v_mov_b32_e32 v85, v104
	v_mov_b32_e32 v87, v105
	v_mov_b32_e32 v89, v106
	v_mov_b32_e32 v91, v107
	v_pk_add_f32 v[84:85], v[84:85], v[86:87]
	v_pk_add_f32 v[86:87], v[88:89], v[90:91]
	s_nop 0
	v_pk_add_f32 v[84:85], v[84:85], v[86:87]
	s_nop 0
	v_add_f32_e32 v9, v84, v85
	s_waitcnt lgkmcnt(0)
; #define LAS __attribute__((address_space(3)))
; __device__ __forceinline__ float bf_lo(unsigned u) { return __uint_as_float(u << 16); }
; __device__ __forceinline__ float bf_hi(unsigned u) { return __uint_as_float(u & 0xffff0000u); }
; __device__ __forceinline__ void ln_affine_l(f32x4 (&v)[4], const LAS float* gL, const LAS float* bL, int lane) {
;     float s = 0.f;
; #pragma unroll
;     for (int j = 0; j < 4; ++j) s += (v[j].x + v[j].y) + (v[j].z + v[j].w);
;     const float mean = wave_sum(s) * (1.f / D_); float s2 = 0.f;
; #pragma unroll
;     for (int j = 0; j < 4; ++j) { v[j] = v[j] - mean; s2 += (v[j].x * v[j].x + v[j].y * v[j].y) + (v[j].z * v[j].z + v[j].w * v[j].w); }
;     const float rstd = 1.f / sqrtf(wave_sum(s2) * (1.f / D_) + LN_EPS_);
; #pragma unroll
;     for (int j = 0; j < 4; ++j) v[j] = v[j] * rstd * *(const LAS f32x4*)(gL + 4 * lane + 256 * j) + *(const LAS f32x4*)(bL + 4 * lane + 256 * j);
; }
; __device__ __forceinline__ void ln1_router_tile(KArgs A, int l, int tile, int lane, const LAS bf16_t* wH) {
;     ...
;         for (int i = 0; i < 8; ++i) { f32x4 hv[4];
; #pragma unroll
;             for (int j = 0; j < 4; ++j) { hv[j].x = bf_lo(hr[i][j].x) * ALPHA_ + bf_lo(mm[i][j].x); hv[j].y = bf_hi(hr[i][j].x) * ALPHA_ + bf_hi(mm[i][j].x); hv[j].z = bf_lo(hr[i][j].y) * ALPHA_ + bf_lo(mm[i][j].y); hv[j].w = bf_hi(hr[i][j].y) * ALPHA_ + bf_hi(mm[i][j].y); }
;             ln_affine_l(hv, gL, bL, lane); store_row_bf16(HB + (size_t)(r0 + i) * D_, hv, lane); }
	s_nop 1
	v_add_f32_dpp v9, v9, v9 quad_perm:[1,0,3,2] row_mask:0xf bank_mask:0xf
	s_waitcnt lgkmcnt(0)
	s_nop 1
	v_add_f32_dpp v9, v9, v9 quad_perm:[2,3,0,1] row_mask:0xf bank_mask:0xf
	s_waitcnt lgkmcnt(0)
	s_nop 1
	v_add_f32_dpp v9, v9, v9 row_half_mirror row_mask:0xf bank_mask:0xf
	s_waitcnt lgkmcnt(0)
	s_nop 1
	v_add_f32_dpp v9, v9, v9 row_mirror row_mask:0xf bank_mask:0xf
	s_waitcnt lgkmcnt(0)
	v_mov_b32_e32 v84, v9
	s_nop 1
	v_permlane16_swap_b32 v9, v84
	v_add_f32_e32 v9, v9, v84
	s_waitcnt lgkmcnt(0)
	v_mov_b32_e32 v84, v9
	s_nop 1
	v_permlane32_swap_b32 v9, v84
	v_add_f32_e32 v9, v9, v84
	v_fmamk_f32 v101, v9, 0xba800000, v101
	v_fmac_f32_e32 v100, 0xba800000, v9
	v_fmamk_f32 v97, v9, 0xba800000, v97
	v_fmac_f32_e32 v96, 0xba800000, v9
	v_pk_mul_f32 v[84:85], v[96:97], v[96:97]
	v_pk_mul_f32 v[86:87], v[100:101], v[100:101]
	v_fmamk_f32 v99, v9, 0xba800000, v99
	v_pk_mov_b32 v[88:89], v[86:87], v[84:85] op_sel:[1,0]
	v_mov_b32_e32 v87, v85
	v_pk_add_f32 v[84:85], v[88:89], v[86:87]
	v_fmac_f32_e32 v98, 0xba800000, v9
	v_fmamk_f32 v93, v9, 0xba800000, v93
	v_fmac_f32_e32 v92, 0xba800000, v9
	v_pk_add_f32 v[84:85], v[84:85], v[84:85] op_sel_hi:[0,1]
	v_pk_mul_f32 v[86:87], v[92:93], v[92:93]
	v_pk_mul_f32 v[88:89], v[98:99], v[98:99]
	v_fmac_f32_e32 v94, 0xba800000, v9
	v_pk_mov_b32 v[90:91], v[88:89], v[86:87] op_sel:[1,0]
	v_mov_b32_e32 v89, v87
	v_fmamk_f32 v95, v9, 0xba800000, v95
	v_fmac_f32_e32 v102, 0xba800000, v9
	v_mul_f32_e32 v84, v94, v94
	v_pk_add_f32 v[86:87], v[90:91], v[88:89]
	v_fmamk_f32 v103, v9, 0xba800000, v103
	v_pk_fma_f32 v[88:89], v[94:95], v[94:95], v[84:85] op_sel_hi:[1,1,0]
	v_mul_f32_e32 v84, v102, v102
	v_pk_add_f32 v[86:87], v[86:87], v[86:87] op_sel_hi:[0,1]
	v_pk_fma_f32 v[90:91], v[102:103], v[102:103], v[84:85] op_sel_hi:[1,1,0]
	v_fmamk_f32 v107, v9, 0xba800000, v107
	v_fmac_f32_e32 v106, 0xba800000, v9
	v_fmamk_f32 v105, v9, 0xba800000, v105
	v_fmac_f32_e32 v104, 0xba800000, v9
	v_mul_f32_e32 v88, v104, v104
	v_mul_f32_e32 v90, v105, v105
	v_mul_f32_e32 v84, v106, v106
	v_mul_f32_e32 v86, v107, v107
	v_pk_add_f32 v[88:89], v[88:89], v[90:91]
	v_pk_add_f32 v[84:85], v[84:85], v[86:87]
	s_nop 0
	v_pk_add_f32 v[84:85], v[88:89], v[84:85]
	s_nop 0
	v_add_f32_e32 v9, v84, v85
	s_waitcnt lgkmcnt(0)
	s_nop 1
	v_add_f32_dpp v9, v9, v9 quad_perm:[1,0,3,2] row_mask:0xf bank_mask:0xf
	s_waitcnt lgkmcnt(0)
	s_nop 1
	v_add_f32_dpp v9, v9, v9 quad_perm:[2,3,0,1] row_mask:0xf bank_mask:0xf
	s_waitcnt lgkmcnt(0)
	s_nop 1
	v_add_f32_dpp v9, v9, v9 row_half_mirror row_mask:0xf bank_mask:0xf
	s_waitcnt lgkmcnt(0)
	s_nop 1
	v_add_f32_dpp v9, v9, v9 row_mirror row_mask:0xf bank_mask:0xf
	s_waitcnt lgkmcnt(0)
	v_mov_b32_e32 v84, v9
	s_nop 1
	v_permlane16_swap_b32 v9, v84
	v_add_f32_e32 v9, v9, v84
	s_waitcnt lgkmcnt(0)
	v_mov_b32_e32 v84, v9
	s_nop 1
	v_permlane32_swap_b32 v9, v84
	v_add_f32_e32 v9, v9, v84
	v_fmamk_f32 v9, v9, 0x3a800000, v227
	v_cmp_gt_f32_e32 vcc, s47, v9
	v_mul_f32_e32 v84, 0x4f800000, v9
	s_nop 0
	v_cndmask_b32_e32 v9, v9, v84, vcc
	v_sqrt_f32_e32 v84, v9
	s_nop 0
	v_add_u32_e32 v85, -1, v84
	v_fma_f32 v86, -v85, v84, v9
	v_cmp_ge_f32_e64 s[8:9], 0, v86
	v_add_u32_e32 v86, 1, v84
	s_nop 0
	v_cndmask_b32_e64 v85, v84, v85, s[8:9]
	v_fma_f32 v84, -v86, v84, v9
	v_cmp_lt_f32_e64 s[8:9], 0, v84
	s_nop 1
	v_cndmask_b32_e64 v84, v85, v86, s[8:9]
	v_mul_f32_e32 v85, 0x37800000, v84
	v_cndmask_b32_e32 v84, v84, v85, vcc
	v_cmp_class_f32_e32 vcc, v9, v228
	s_nop 1
	v_cndmask_b32_e32 v9, v84, v9, vcc
	v_div_scale_f32 v84, s[0:1], v9, v9, 1.0
	v_rcp_f32_e32 v85, v84
	s_nop 0
	v_fma_f32 v86, -v84, v85, 1.0
	v_fmac_f32_e32 v85, v86, v85
	v_div_scale_f32 v86, vcc, 1.0, v9, 1.0
	v_mul_f32_e32 v87, v86, v85
	v_fma_f32 v88, -v84, v87, v86
	v_fmac_f32_e32 v87, v88, v85
	v_fma_f32 v84, -v84, v87, v86
	v_div_fmas_f32 v84, v84, v85, v87
	v_div_fixup_f32 v108, v84, v9, 1.0
	ds_read_b128 v[84:87], v152
	ds_read_b128 v[88:91], v153
	v_pk_mul_f32 v[100:101], v[100:101], v[108:109] op_sel_hi:[1,0]
	v_pk_mul_f32 v[96:97], v[96:97], v[108:109] op_sel_hi:[1,0]
	v_pk_mul_f32 v[98:99], v[98:99], v[108:109] op_sel_hi:[1,0]
	v_pk_mul_f32 v[92:93], v[92:93], v[108:109] op_sel_hi:[1,0]
	s_waitcnt lgkmcnt(0)
	v_pk_fma_f32 v[96:97], v[86:87], v[96:97], v[90:91]
	v_pk_fma_f32 v[100:101], v[84:85], v[100:101], v[88:89]
	ds_read_b128 v[84:87], v152 offset:1024
	ds_read_b128 v[88:91], v153 offset:1024
	v_pk_mul_f32 v[94:95], v[94:95], v[108:109] op_sel_hi:[1,0]
	v_pk_mul_f32 v[102:103], v[102:103], v[108:109] op_sel_hi:[1,0]
	v_pk_mul_f32 v[104:105], v[104:105], v[108:109] op_sel_hi:[1,0]
	v_pk_mul_f32 v[106:107], v[106:107], v[108:109] op_sel_hi:[1,0]
	s_waitcnt lgkmcnt(0)
	v_pk_fma_f32 v[92:93], v[86:87], v[92:93], v[90:91]
	v_pk_fma_f32 v[98:99], v[84:85], v[98:99], v[88:89]
	ds_read_b128 v[84:87], v152 offset:2048
	ds_read_b128 v[88:91], v153 offset:2048
	s_waitcnt lgkmcnt(0)
	v_pk_fma_f32 v[102:103], v[86:87], v[102:103], v[90:91]
	v_pk_fma_f32 v[94:95], v[84:85], v[94:95], v[88:89]
	ds_read_b128 v[84:87], v152 offset:3072
	ds_read_b128 v[88:91], v153 offset:3072
	s_waitcnt lgkmcnt(0)
	v_pk_fma_f32 v[84:85], v[84:85], v[104:105], v[88:89]
	v_cvt_pk_bf16_f32 v88, v100, v101
	v_cvt_pk_bf16_f32 v89, v96, v97
	global_store_dwordx2 v[82:83], v[88:89], off
	v_cvt_pk_bf16_f32 v88, v98, v99
	v_cvt_pk_bf16_f32 v89, v92, v93
	v_pk_fma_f32 v[86:87], v[86:87], v[106:107], v[90:91]
	global_store_dwordx2 v[82:83], v[88:89], off offset:512
	v_cvt_pk_bf16_f32 v88, v94, v95
	v_cvt_pk_bf16_f32 v89, v102, v103
	global_store_dwordx2 v[82:83], v[88:89], off offset:1024
	v_cvt_pk_bf16_f32 v84, v84, v85
	v_cvt_pk_bf16_f32 v85, v86, v87
	global_store_dwordx2 v[82:83], v[84:85], off offset:1536
	s_waitcnt vmcnt(47)
; #define LAS __attribute__((address_space(3)))
; __device__ __forceinline__ float bf_lo(unsigned u) { return __uint_as_float(u << 16); }
; __device__ __forceinline__ float bf_hi(unsigned u) { return __uint_as_float(u & 0xffff0000u); }
; __device__ __forceinline__ void ln_affine_l(f32x4 (&v)[4], const LAS float* gL, const LAS float* bL, int lane) {
;     float s = 0.f;
; #pragma unroll
;     for (int j = 0; j < 4; ++j) s += (v[j].x + v[j].y) + (v[j].z + v[j].w);
;     const float mean = wave_sum(s) * (1.f / D_); float s2 = 0.f;
; #pragma unroll
;     for (int j = 0; j < 4; ++j) { v[j] = v[j] - mean; s2 += (v[j].x * v[j].x + v[j].y * v[j].y) + (v[j].z * v[j].z + v[j].w * v[j].w); }
;     const float rstd = 1.f / sqrtf(wave_sum(s2) * (1.f / D_) + LN_EPS_);
; #pragma unroll
;     for (int j = 0; j < 4; ++j) v[j] = v[j] * rstd * *(const LAS f32x4*)(gL + 4 * lane + 256 * j) + *(const LAS f32x4*)(bL + 4 * lane + 256 * j);
; }
; __device__ __forceinline__ void ln1_router_tile(KArgs A, int l, int tile, int lane, const LAS bf16_t* wH) {
;     ...
;         for (int i = 0; i < 8; ++i) { f32x4 hv[4];
; #pragma unroll
;             for (int j = 0; j < 4; ++j) { hv[j].x = bf_lo(hr[i][j].x) * ALPHA_ + bf_lo(mm[i][j].x); hv[j].y = bf_hi(hr[i][j].x) * ALPHA_ + bf_hi(mm[i][j].x); hv[j].z = bf_lo(hr[i][j].y) * ALPHA_ + bf_lo(mm[i][j].y); hv[j].w = bf_hi(hr[i][j].y) * ALPHA_ + bf_hi(mm[i][j].y); }
;             ln_affine_l(hv, gL, bL, lane); store_row_bf16(HB + (size_t)(r0 + i) * D_, hv, lane); }
	v_lshlrev_b32_e32 v82, 16, v80
	v_and_b32_e32 v83, 0xffff0000, v80
	s_waitcnt vmcnt(46)
	v_lshlrev_b32_e32 v84, 16, v78
	v_and_b32_e32 v85, 0xffff0000, v78
	v_lshlrev_b32_e32 v80, 16, v81
	v_and_b32_e32 v81, 0xffff0000, v81
	v_lshlrev_b32_e32 v78, 16, v79
	v_and_b32_e32 v79, 0xffff0000, v79
	v_pk_fma_f32 v[82:83], v[82:83], s[78:79], v[84:85] op_sel_hi:[1,0,1]
	v_pk_fma_f32 v[78:79], v[80:81], s[78:79], v[78:79] op_sel_hi:[1,0,1]
	s_waitcnt vmcnt(45)
	v_lshlrev_b32_e32 v80, 16, v76
	v_and_b32_e32 v81, 0xffff0000, v76
	s_waitcnt vmcnt(44)
	v_lshlrev_b32_e32 v84, 16, v74
	v_and_b32_e32 v85, 0xffff0000, v74
	v_lshlrev_b32_e32 v76, 16, v77
	v_and_b32_e32 v77, 0xffff0000, v77
	v_lshlrev_b32_e32 v74, 16, v75
	v_and_b32_e32 v75, 0xffff0000, v75
	v_pk_fma_f32 v[80:81], v[80:81], s[78:79], v[84:85] op_sel_hi:[1,0,1]
	v_pk_fma_f32 v[74:75], v[76:77], s[78:79], v[74:75] op_sel_hi:[1,0,1]
	s_waitcnt vmcnt(43)
	v_lshlrev_b32_e32 v76, 16, v72
	v_and_b32_e32 v77, 0xffff0000, v72
	s_waitcnt vmcnt(42)
	v_lshlrev_b32_e32 v84, 16, v70
	v_and_b32_e32 v85, 0xffff0000, v70
	v_lshlrev_b32_e32 v72, 16, v73
	v_and_b32_e32 v73, 0xffff0000, v73
	v_lshlrev_b32_e32 v70, 16, v71
	v_and_b32_e32 v71, 0xffff0000, v71
	v_pk_fma_f32 v[76:77], v[76:77], s[78:79], v[84:85] op_sel_hi:[1,0,1]
	v_pk_fma_f32 v[84:85], v[72:73], s[78:79], v[70:71] op_sel_hi:[1,0,1]
	s_waitcnt vmcnt(41)
	v_lshlrev_b32_e32 v70, 16, v68
	v_and_b32_e32 v71, 0xffff0000, v68
	s_waitcnt vmcnt(40)
	v_lshlrev_b32_e32 v72, 16, v66
	v_and_b32_e32 v73, 0xffff0000, v66
	v_lshlrev_b32_e32 v68, 16, v69
	v_and_b32_e32 v69, 0xffff0000, v69
	v_lshlrev_b32_e32 v66, 16, v67
	v_and_b32_e32 v67, 0xffff0000, v67
	v_pk_fma_f32 v[88:89], v[68:69], s[78:79], v[66:67] op_sel_hi:[1,0,1]
	v_mov_b32_e32 v66, v82
	v_mov_b32_e32 v67, v78
	v_mov_b32_e32 v68, v83
	v_mov_b32_e32 v69, v79
	v_pk_fma_f32 v[86:87], v[70:71], s[78:79], v[72:73] op_sel_hi:[1,0,1]
	v_pk_add_f32 v[66:67], v[66:67], v[68:69]
	v_mov_b32_e32 v68, v80
	v_mov_b32_e32 v69, v74
	v_mov_b32_e32 v70, v81
	v_mov_b32_e32 v71, v75
	v_pk_add_f32 v[68:69], v[68:69], v[70:71]
	v_add_f32_e32 v9, v66, v67
	v_pk_add_f32 v[68:69], v[68:69], v[68:69] op_sel:[0,1] op_sel_hi:[1,0]
	v_pk_add_f32 v[70:71], v[76:77], v[76:77] op_sel:[0,1] op_sel_hi:[1,0]
	v_pk_add_f32 v[72:73], v[84:85], v[84:85] op_sel:[0,1] op_sel_hi:[1,0]
	v_add_f32_e32 v66, 0, v9
	v_mov_b32_e32 v67, v86
	v_mov_b32_e32 v69, v87
	v_mov_b32_e32 v71, v88
	v_mov_b32_e32 v73, v89
	v_pk_add_f32 v[66:67], v[66:67], v[68:69]
	v_pk_add_f32 v[68:69], v[70:71], v[72:73]
	s_nop 0
	v_pk_add_f32 v[66:67], v[66:67], v[68:69]
	s_nop 0
	v_add_f32_e32 v9, v66, v67
	s_waitcnt lgkmcnt(0)
	s_nop 1
	v_add_f32_dpp v9, v9, v9 quad_perm:[1,0,3,2] row_mask:0xf bank_mask:0xf
	s_waitcnt lgkmcnt(0)
	s_nop 1
	v_add_f32_dpp v9, v9, v9 quad_perm:[2,3,0,1] row_mask:0xf bank_mask:0xf
	s_waitcnt lgkmcnt(0)
	s_nop 1
	v_add_f32_dpp v9, v9, v9 row_half_mirror row_mask:0xf bank_mask:0xf
	s_waitcnt lgkmcnt(0)
	s_nop 1
	v_add_f32_dpp v9, v9, v9 row_mirror row_mask:0xf bank_mask:0xf
	s_waitcnt lgkmcnt(0)
	v_mov_b32_e32 v66, v9
	s_nop 1
	v_permlane16_swap_b32 v9, v66
	v_add_f32_e32 v9, v9, v66
	s_waitcnt lgkmcnt(0)
	v_mov_b32_e32 v66, v9
	s_nop 1
	v_permlane32_swap_b32 v9, v66
	v_add_f32_e32 v9, v9, v66
	v_fmamk_f32 v83, v9, 0xba800000, v83
	v_fmac_f32_e32 v82, 0xba800000, v9
	v_fmamk_f32 v79, v9, 0xba800000, v79
	v_fmac_f32_e32 v78, 0xba800000, v9
	v_pk_mul_f32 v[66:67], v[78:79], v[78:79]
	v_pk_mul_f32 v[68:69], v[82:83], v[82:83]
	v_fmamk_f32 v81, v9, 0xba800000, v81
	v_pk_mov_b32 v[70:71], v[68:69], v[66:67] op_sel:[1,0]
	v_mov_b32_e32 v69, v67
	v_pk_add_f32 v[66:67], v[70:71], v[68:69]
	v_fmac_f32_e32 v80, 0xba800000, v9
	v_fmamk_f32 v75, v9, 0xba800000, v75
	v_fmac_f32_e32 v74, 0xba800000, v9
	v_pk_add_f32 v[66:67], v[66:67], v[66:67] op_sel_hi:[0,1]
	v_pk_mul_f32 v[68:69], v[74:75], v[74:75]
	v_pk_mul_f32 v[70:71], v[80:81], v[80:81]
	v_fmac_f32_e32 v76, 0xba800000, v9
	v_pk_mov_b32 v[72:73], v[70:71], v[68:69] op_sel:[1,0]
	v_mov_b32_e32 v71, v69
	v_fmamk_f32 v77, v9, 0xba800000, v77
	v_fmac_f32_e32 v84, 0xba800000, v9
	v_mul_f32_e32 v66, v76, v76
	v_pk_add_f32 v[68:69], v[72:73], v[70:71]
	v_fmamk_f32 v85, v9, 0xba800000, v85
	v_pk_fma_f32 v[70:71], v[76:77], v[76:77], v[66:67] op_sel_hi:[1,1,0]
	v_mul_f32_e32 v66, v84, v84
	v_pk_add_f32 v[68:69], v[68:69], v[68:69] op_sel_hi:[0,1]
	v_pk_fma_f32 v[72:73], v[84:85], v[84:85], v[66:67] op_sel_hi:[1,1,0]
	v_fmamk_f32 v89, v9, 0xba800000, v89
	v_fmac_f32_e32 v88, 0xba800000, v9
	v_fmamk_f32 v87, v9, 0xba800000, v87
	v_fmac_f32_e32 v86, 0xba800000, v9
	v_mul_f32_e32 v70, v86, v86
	v_mul_f32_e32 v72, v87, v87
	v_mul_f32_e32 v66, v88, v88
	v_mul_f32_e32 v68, v89, v89
	v_pk_add_f32 v[70:71], v[70:71], v[72:73]
	v_pk_add_f32 v[66:67], v[66:67], v[68:69]
	s_nop 0
	v_pk_add_f32 v[66:67], v[70:71], v[66:67]
	s_nop 0
	v_add_f32_e32 v9, v66, v67
	s_waitcnt lgkmcnt(0)
	s_nop 1
	v_add_f32_dpp v9, v9, v9 quad_perm:[1,0,3,2] row_mask:0xf bank_mask:0xf
	s_waitcnt lgkmcnt(0)
	s_nop 1
	v_add_f32_dpp v9, v9, v9 quad_perm:[2,3,0,1] row_mask:0xf bank_mask:0xf
	s_waitcnt lgkmcnt(0)
	s_nop 1
	v_add_f32_dpp v9, v9, v9 row_half_mirror row_mask:0xf bank_mask:0xf
	s_waitcnt lgkmcnt(0)
	s_nop 1
	v_add_f32_dpp v9, v9, v9 row_mirror row_mask:0xf bank_mask:0xf
	s_waitcnt lgkmcnt(0)
	v_mov_b32_e32 v66, v9
	s_nop 1
	v_permlane16_swap_b32 v9, v66
	v_add_f32_e32 v9, v9, v66
	s_waitcnt lgkmcnt(0)
; #define LAS __attribute__((address_space(3)))
; __device__ __forceinline__ float bf_lo(unsigned u) { return __uint_as_float(u << 16); }
; __device__ __forceinline__ float bf_hi(unsigned u) { return __uint_as_float(u & 0xffff0000u); }
; __device__ __forceinline__ void ln_affine_l(f32x4 (&v)[4], const LAS float* gL, const LAS float* bL, int lane) {
;     float s = 0.f;
; #pragma unroll
;     for (int j = 0; j < 4; ++j) s += (v[j].x + v[j].y) + (v[j].z + v[j].w);
;     const float mean = wave_sum(s) * (1.f / D_); float s2 = 0.f;
; #pragma unroll
;     for (int j = 0; j < 4; ++j) { v[j] = v[j] - mean; s2 += (v[j].x * v[j].x + v[j].y * v[j].y) + (v[j].z * v[j].z + v[j].w * v[j].w); }
;     const float rstd = 1.f / sqrtf(wave_sum(s2) * (1.f / D_) + LN_EPS_);
; #pragma unroll
;     for (int j = 0; j < 4; ++j) v[j] = v[j] * rstd * *(const LAS f32x4*)(gL + 4 * lane + 256 * j) + *(const LAS f32x4*)(bL + 4 * lane + 256 * j);
; }
; __device__ __forceinline__ void ln1_router_tile(KArgs A, int l, int tile, int lane, const LAS bf16_t* wH) {
;     ...
;         for (int i = 0; i < 8; ++i) { f32x4 hv[4];
; #pragma unroll
;             for (int j = 0; j < 4; ++j) { hv[j].x = bf_lo(hr[i][j].x) * ALPHA_ + bf_lo(mm[i][j].x); hv[j].y = bf_hi(hr[i][j].x) * ALPHA_ + bf_hi(mm[i][j].x); hv[j].z = bf_lo(hr[i][j].y) * ALPHA_ + bf_lo(mm[i][j].y); hv[j].w = bf_hi(hr[i][j].y) * ALPHA_ + bf_hi(mm[i][j].y); }
;             ln_affine_l(hv, gL, bL, lane); store_row_bf16(HB + (size_t)(r0 + i) * D_, hv, lane); }
	v_mov_b32_e32 v66, v9
	s_nop 1
	v_permlane32_swap_b32 v9, v66
	v_add_f32_e32 v9, v9, v66
	v_fmamk_f32 v9, v9, 0x3a800000, v227
	v_cmp_gt_f32_e32 vcc, s47, v9
	v_mul_f32_e32 v66, 0x4f800000, v9
	s_nop 0
	v_cndmask_b32_e32 v9, v9, v66, vcc
	v_sqrt_f32_e32 v66, v9
	s_nop 0
	v_add_u32_e32 v67, -1, v66
	v_fma_f32 v68, -v67, v66, v9
	v_cmp_ge_f32_e64 s[8:9], 0, v68
	v_add_u32_e32 v68, 1, v66
	s_nop 0
	v_cndmask_b32_e64 v67, v66, v67, s[8:9]
	v_fma_f32 v66, -v68, v66, v9
	v_cmp_lt_f32_e64 s[8:9], 0, v66
	s_nop 1
	v_cndmask_b32_e64 v66, v67, v68, s[8:9]
	v_mul_f32_e32 v67, 0x37800000, v66
	v_cndmask_b32_e32 v66, v66, v67, vcc
	v_cmp_class_f32_e32 vcc, v9, v228
	s_nop 1
	v_cndmask_b32_e32 v9, v66, v9, vcc
	v_div_scale_f32 v66, s[0:1], v9, v9, 1.0
	v_rcp_f32_e32 v67, v66
	s_nop 0
	v_fma_f32 v68, -v66, v67, 1.0
	v_fmac_f32_e32 v67, v68, v67
	v_div_scale_f32 v68, vcc, 1.0, v9, 1.0
	v_mul_f32_e32 v69, v68, v67
	v_fma_f32 v70, -v66, v69, v68
	v_fmac_f32_e32 v69, v70, v67
	v_fma_f32 v66, -v66, v69, v68
	v_div_fmas_f32 v66, v66, v67, v69
	v_div_fixup_f32 v90, v66, v9, 1.0
	ds_read_b128 v[66:69], v152
	ds_read_b128 v[70:73], v153
	v_pk_mul_f32 v[82:83], v[82:83], v[90:91] op_sel_hi:[1,0]
	v_pk_mul_f32 v[78:79], v[78:79], v[90:91] op_sel_hi:[1,0]
	v_pk_mul_f32 v[80:81], v[80:81], v[90:91] op_sel_hi:[1,0]
	v_pk_mul_f32 v[74:75], v[74:75], v[90:91] op_sel_hi:[1,0]
	s_waitcnt lgkmcnt(0)
	v_pk_fma_f32 v[78:79], v[68:69], v[78:79], v[72:73]
	v_pk_fma_f32 v[82:83], v[66:67], v[82:83], v[70:71]
	ds_read_b128 v[66:69], v152 offset:1024
	ds_read_b128 v[70:73], v153 offset:1024
	v_pk_mul_f32 v[76:77], v[76:77], v[90:91] op_sel_hi:[1,0]
	v_pk_mul_f32 v[84:85], v[84:85], v[90:91] op_sel_hi:[1,0]
	v_pk_mul_f32 v[86:87], v[86:87], v[90:91] op_sel_hi:[1,0]
	v_pk_mul_f32 v[88:89], v[88:89], v[90:91] op_sel_hi:[1,0]
	s_waitcnt lgkmcnt(0)
	v_pk_fma_f32 v[74:75], v[68:69], v[74:75], v[72:73]
	v_pk_fma_f32 v[80:81], v[66:67], v[80:81], v[70:71]
	ds_read_b128 v[66:69], v152 offset:2048
	ds_read_b128 v[70:73], v153 offset:2048
	s_waitcnt lgkmcnt(0)
	v_pk_fma_f32 v[84:85], v[68:69], v[84:85], v[72:73]
	v_pk_fma_f32 v[76:77], v[66:67], v[76:77], v[70:71]
	ds_read_b128 v[66:69], v152 offset:3072
	ds_read_b128 v[70:73], v153 offset:3072
	s_waitcnt lgkmcnt(0)
	v_pk_fma_f32 v[66:67], v[66:67], v[86:87], v[70:71]
	v_cvt_pk_bf16_f32 v70, v82, v83
	v_cvt_pk_bf16_f32 v71, v78, v79
	global_store_dwordx2 v[64:65], v[70:71], off
	v_cvt_pk_bf16_f32 v70, v80, v81
	v_cvt_pk_bf16_f32 v71, v74, v75
	v_pk_fma_f32 v[68:69], v[68:69], v[88:89], v[72:73]
	global_store_dwordx2 v[64:65], v[70:71], off offset:512
	v_cvt_pk_bf16_f32 v70, v76, v77
	v_cvt_pk_bf16_f32 v71, v84, v85
	global_store_dwordx2 v[64:65], v[70:71], off offset:1024
	v_cvt_pk_bf16_f32 v66, v66, v67
	v_cvt_pk_bf16_f32 v67, v68, v69
	global_store_dwordx2 v[64:65], v[66:67], off offset:1536
	s_waitcnt vmcnt(43)
	v_lshlrev_b32_e32 v64, 16, v62
	v_and_b32_e32 v65, 0xffff0000, v62
	s_waitcnt vmcnt(42)
	v_lshlrev_b32_e32 v66, 16, v60
	v_and_b32_e32 v67, 0xffff0000, v60
	v_lshlrev_b32_e32 v62, 16, v63
	v_and_b32_e32 v63, 0xffff0000, v63
	v_lshlrev_b32_e32 v60, 16, v61
	v_and_b32_e32 v61, 0xffff0000, v61
	v_pk_fma_f32 v[64:65], v[64:65], s[78:79], v[66:67] op_sel_hi:[1,0,1]
	v_pk_fma_f32 v[60:61], v[62:63], s[78:79], v[60:61] op_sel_hi:[1,0,1]
	s_waitcnt vmcnt(41)
	v_lshlrev_b32_e32 v62, 16, v58
	v_and_b32_e32 v63, 0xffff0000, v58
	s_waitcnt vmcnt(40)
	v_lshlrev_b32_e32 v66, 16, v56
	v_and_b32_e32 v67, 0xffff0000, v56
	v_lshlrev_b32_e32 v58, 16, v59
	v_and_b32_e32 v59, 0xffff0000, v59
	v_lshlrev_b32_e32 v56, 16, v57
	v_and_b32_e32 v57, 0xffff0000, v57
	v_pk_fma_f32 v[62:63], v[62:63], s[78:79], v[66:67] op_sel_hi:[1,0,1]
	v_pk_fma_f32 v[56:57], v[58:59], s[78:79], v[56:57] op_sel_hi:[1,0,1]
	s_waitcnt vmcnt(39)
	v_lshlrev_b32_e32 v58, 16, v54
	v_and_b32_e32 v59, 0xffff0000, v54
	s_waitcnt vmcnt(38)
	v_lshlrev_b32_e32 v66, 16, v52
	v_and_b32_e32 v67, 0xffff0000, v52
	v_lshlrev_b32_e32 v54, 16, v55
	v_and_b32_e32 v55, 0xffff0000, v55
	v_lshlrev_b32_e32 v52, 16, v53
	v_and_b32_e32 v53, 0xffff0000, v53
	v_pk_fma_f32 v[58:59], v[58:59], s[78:79], v[66:67] op_sel_hi:[1,0,1]
	v_pk_fma_f32 v[66:67], v[54:55], s[78:79], v[52:53] op_sel_hi:[1,0,1]
	s_waitcnt vmcnt(37)
	v_lshlrev_b32_e32 v52, 16, v50
	v_and_b32_e32 v53, 0xffff0000, v50
	s_waitcnt vmcnt(36)
	v_lshlrev_b32_e32 v54, 16, v48
	v_and_b32_e32 v55, 0xffff0000, v48
	v_lshlrev_b32_e32 v50, 16, v51
	v_and_b32_e32 v51, 0xffff0000, v51
	v_lshlrev_b32_e32 v48, 16, v49
	v_and_b32_e32 v49, 0xffff0000, v49
	v_pk_fma_f32 v[70:71], v[50:51], s[78:79], v[48:49] op_sel_hi:[1,0,1]
	v_mov_b32_e32 v48, v64
	v_mov_b32_e32 v49, v60
	v_mov_b32_e32 v50, v65
	v_mov_b32_e32 v51, v61
	v_pk_fma_f32 v[68:69], v[52:53], s[78:79], v[54:55] op_sel_hi:[1,0,1]
	v_pk_add_f32 v[48:49], v[48:49], v[50:51]
	v_mov_b32_e32 v50, v62
	v_mov_b32_e32 v51, v56
	v_mov_b32_e32 v52, v63
	v_mov_b32_e32 v53, v57
	v_pk_add_f32 v[50:51], v[50:51], v[52:53]
	v_add_f32_e32 v9, v48, v49
	v_pk_add_f32 v[50:51], v[50:51], v[50:51] op_sel:[0,1] op_sel_hi:[1,0]
	v_pk_add_f32 v[52:53], v[58:59], v[58:59] op_sel:[0,1] op_sel_hi:[1,0]
	v_pk_add_f32 v[54:55], v[66:67], v[66:67] op_sel:[0,1] op_sel_hi:[1,0]
	v_add_f32_e32 v48, 0, v9
	v_mov_b32_e32 v49, v68
	v_mov_b32_e32 v51, v69
	v_mov_b32_e32 v53, v70
	v_mov_b32_e32 v55, v71
	v_pk_add_f32 v[48:49], v[48:49], v[50:51]
	v_pk_add_f32 v[50:51], v[52:53], v[54:55]
	s_nop 0
	v_pk_add_f32 v[48:49], v[48:49], v[50:51]
	s_nop 0
	v_add_f32_e32 v9, v48, v49
	s_waitcnt lgkmcnt(0)
	s_nop 1
	v_add_f32_dpp v9, v9, v9 quad_perm:[1,0,3,2] row_mask:0xf bank_mask:0xf
	s_waitcnt lgkmcnt(0)
; #define LAS __attribute__((address_space(3)))
; __device__ __forceinline__ float bf_lo(unsigned u) { return __uint_as_float(u << 16); }
; __device__ __forceinline__ float bf_hi(unsigned u) { return __uint_as_float(u & 0xffff0000u); }
; __device__ __forceinline__ void ln_affine_l(f32x4 (&v)[4], const LAS float* gL, const LAS float* bL, int lane) {
;     float s = 0.f;
; #pragma unroll
;     for (int j = 0; j < 4; ++j) s += (v[j].x + v[j].y) + (v[j].z + v[j].w);
;     const float mean = wave_sum(s) * (1.f / D_); float s2 = 0.f;
; #pragma unroll
;     for (int j = 0; j < 4; ++j) { v[j] = v[j] - mean; s2 += (v[j].x * v[j].x + v[j].y * v[j].y) + (v[j].z * v[j].z + v[j].w * v[j].w); }
;     const float rstd = 1.f / sqrtf(wave_sum(s2) * (1.f / D_) + LN_EPS_);
; #pragma unroll
;     for (int j = 0; j < 4; ++j) v[j] = v[j] * rstd * *(const LAS f32x4*)(gL + 4 * lane + 256 * j) + *(const LAS f32x4*)(bL + 4 * lane + 256 * j);
; }
; __device__ __forceinline__ void ln1_router_tile(KArgs A, int l, int tile, int lane, const LAS bf16_t* wH) {
;     ...
;         for (int i = 0; i < 8; ++i) { f32x4 hv[4];
; #pragma unroll
;             for (int j = 0; j < 4; ++j) { hv[j].x = bf_lo(hr[i][j].x) * ALPHA_ + bf_lo(mm[i][j].x); hv[j].y = bf_hi(hr[i][j].x) * ALPHA_ + bf_hi(mm[i][j].x); hv[j].z = bf_lo(hr[i][j].y) * ALPHA_ + bf_lo(mm[i][j].y); hv[j].w = bf_hi(hr[i][j].y) * ALPHA_ + bf_hi(mm[i][j].y); }
;             ln_affine_l(hv, gL, bL, lane); store_row_bf16(HB + (size_t)(r0 + i) * D_, hv, lane); }
	s_nop 1
	v_add_f32_dpp v9, v9, v9 quad_perm:[2,3,0,1] row_mask:0xf bank_mask:0xf
	s_waitcnt lgkmcnt(0)
	s_nop 1
	v_add_f32_dpp v9, v9, v9 row_half_mirror row_mask:0xf bank_mask:0xf
	s_waitcnt lgkmcnt(0)
	s_nop 1
	v_add_f32_dpp v9, v9, v9 row_mirror row_mask:0xf bank_mask:0xf
	s_waitcnt lgkmcnt(0)
	v_mov_b32_e32 v48, v9
	s_nop 1
	v_permlane16_swap_b32 v9, v48
	v_add_f32_e32 v9, v9, v48
	s_waitcnt lgkmcnt(0)
	v_mov_b32_e32 v48, v9
	s_nop 1
	v_permlane32_swap_b32 v9, v48
	v_add_f32_e32 v9, v9, v48
	v_fmamk_f32 v65, v9, 0xba800000, v65
	v_fmac_f32_e32 v64, 0xba800000, v9
	v_fmamk_f32 v61, v9, 0xba800000, v61
	v_fmac_f32_e32 v60, 0xba800000, v9
	v_pk_mul_f32 v[48:49], v[60:61], v[60:61]
	v_pk_mul_f32 v[50:51], v[64:65], v[64:65]
	v_fmamk_f32 v63, v9, 0xba800000, v63
	v_pk_mov_b32 v[52:53], v[50:51], v[48:49] op_sel:[1,0]
	v_mov_b32_e32 v51, v49
	v_pk_add_f32 v[48:49], v[52:53], v[50:51]
	v_fmac_f32_e32 v62, 0xba800000, v9
	v_fmamk_f32 v57, v9, 0xba800000, v57
	v_fmac_f32_e32 v56, 0xba800000, v9
	v_pk_add_f32 v[48:49], v[48:49], v[48:49] op_sel_hi:[0,1]
	v_pk_mul_f32 v[50:51], v[56:57], v[56:57]
	v_pk_mul_f32 v[52:53], v[62:63], v[62:63]
	v_fmac_f32_e32 v58, 0xba800000, v9
	v_pk_mov_b32 v[54:55], v[52:53], v[50:51] op_sel:[1,0]
	v_mov_b32_e32 v53, v51
	v_fmamk_f32 v59, v9, 0xba800000, v59
	v_fmac_f32_e32 v66, 0xba800000, v9
	v_mul_f32_e32 v48, v58, v58
	v_pk_add_f32 v[50:51], v[54:55], v[52:53]
	v_fmamk_f32 v67, v9, 0xba800000, v67
	v_pk_fma_f32 v[52:53], v[58:59], v[58:59], v[48:49] op_sel_hi:[1,1,0]
	v_mul_f32_e32 v48, v66, v66
	v_pk_add_f32 v[50:51], v[50:51], v[50:51] op_sel_hi:[0,1]
	v_pk_fma_f32 v[54:55], v[66:67], v[66:67], v[48:49] op_sel_hi:[1,1,0]
	v_fmamk_f32 v71, v9, 0xba800000, v71
	v_fmac_f32_e32 v70, 0xba800000, v9
	v_fmamk_f32 v69, v9, 0xba800000, v69
	v_fmac_f32_e32 v68, 0xba800000, v9
	v_mul_f32_e32 v52, v68, v68
	v_mul_f32_e32 v54, v69, v69
	v_mul_f32_e32 v48, v70, v70
	v_mul_f32_e32 v50, v71, v71
	v_pk_add_f32 v[52:53], v[52:53], v[54:55]
	v_pk_add_f32 v[48:49], v[48:49], v[50:51]
	s_nop 0
	v_pk_add_f32 v[48:49], v[52:53], v[48:49]
	s_nop 0
	v_add_f32_e32 v9, v48, v49
	s_waitcnt lgkmcnt(0)
	s_nop 1
	v_add_f32_dpp v9, v9, v9 quad_perm:[1,0,3,2] row_mask:0xf bank_mask:0xf
	s_waitcnt lgkmcnt(0)
	s_nop 1
	v_add_f32_dpp v9, v9, v9 quad_perm:[2,3,0,1] row_mask:0xf bank_mask:0xf
	s_waitcnt lgkmcnt(0)
	s_nop 1
	v_add_f32_dpp v9, v9, v9 row_half_mirror row_mask:0xf bank_mask:0xf
	s_waitcnt lgkmcnt(0)
	s_nop 1
	v_add_f32_dpp v9, v9, v9 row_mirror row_mask:0xf bank_mask:0xf
	s_waitcnt lgkmcnt(0)
	v_mov_b32_e32 v48, v9
	s_nop 1
	v_permlane16_swap_b32 v9, v48
	v_add_f32_e32 v9, v9, v48
	s_waitcnt lgkmcnt(0)
	v_mov_b32_e32 v48, v9
	s_nop 1
	v_permlane32_swap_b32 v9, v48
	v_add_f32_e32 v9, v9, v48
	v_fmamk_f32 v9, v9, 0x3a800000, v227
	v_cmp_gt_f32_e32 vcc, s47, v9
	v_mul_f32_e32 v48, 0x4f800000, v9
	s_nop 0
	v_cndmask_b32_e32 v9, v9, v48, vcc
	v_sqrt_f32_e32 v48, v9
	s_nop 0
	v_add_u32_e32 v49, -1, v48
	v_fma_f32 v50, -v49, v48, v9
	v_cmp_ge_f32_e64 s[8:9], 0, v50
	v_add_u32_e32 v50, 1, v48
	s_nop 0
	v_cndmask_b32_e64 v49, v48, v49, s[8:9]
	v_fma_f32 v48, -v50, v48, v9
	v_cmp_lt_f32_e64 s[8:9], 0, v48
	s_nop 1
	v_cndmask_b32_e64 v48, v49, v50, s[8:9]
	v_mul_f32_e32 v49, 0x37800000, v48
	v_cndmask_b32_e32 v48, v48, v49, vcc
	v_cmp_class_f32_e32 vcc, v9, v228
	s_nop 1
	v_cndmask_b32_e32 v9, v48, v9, vcc
	v_div_scale_f32 v48, s[0:1], v9, v9, 1.0
	v_rcp_f32_e32 v49, v48
	s_nop 0
	v_fma_f32 v50, -v48, v49, 1.0
	v_fmac_f32_e32 v49, v50, v49
	v_div_scale_f32 v50, vcc, 1.0, v9, 1.0
	v_mul_f32_e32 v51, v50, v49
	v_fma_f32 v52, -v48, v51, v50
	v_fmac_f32_e32 v51, v52, v49
	v_fma_f32 v48, -v48, v51, v50
	v_div_fmas_f32 v48, v48, v49, v51
	v_div_fixup_f32 v72, v48, v9, 1.0
	ds_read_b128 v[48:51], v152
	ds_read_b128 v[52:55], v153
	v_pk_mul_f32 v[64:65], v[64:65], v[72:73] op_sel_hi:[1,0]
	v_pk_mul_f32 v[60:61], v[60:61], v[72:73] op_sel_hi:[1,0]
	v_pk_mul_f32 v[62:63], v[62:63], v[72:73] op_sel_hi:[1,0]
	v_pk_mul_f32 v[56:57], v[56:57], v[72:73] op_sel_hi:[1,0]
	s_waitcnt lgkmcnt(0)
	v_pk_fma_f32 v[60:61], v[50:51], v[60:61], v[54:55]
	v_pk_fma_f32 v[64:65], v[48:49], v[64:65], v[52:53]
	ds_read_b128 v[48:51], v152 offset:1024
	ds_read_b128 v[52:55], v153 offset:1024
	v_pk_mul_f32 v[58:59], v[58:59], v[72:73] op_sel_hi:[1,0]
	v_pk_mul_f32 v[66:67], v[66:67], v[72:73] op_sel_hi:[1,0]
	v_pk_mul_f32 v[68:69], v[68:69], v[72:73] op_sel_hi:[1,0]
	v_pk_mul_f32 v[70:71], v[70:71], v[72:73] op_sel_hi:[1,0]
	s_waitcnt lgkmcnt(0)
	v_pk_fma_f32 v[56:57], v[50:51], v[56:57], v[54:55]
	v_pk_fma_f32 v[62:63], v[48:49], v[62:63], v[52:53]
	ds_read_b128 v[48:51], v152 offset:2048
	ds_read_b128 v[52:55], v153 offset:2048
	s_waitcnt lgkmcnt(0)
	v_pk_fma_f32 v[66:67], v[50:51], v[66:67], v[54:55]
	v_pk_fma_f32 v[58:59], v[48:49], v[58:59], v[52:53]
	ds_read_b128 v[48:51], v152 offset:3072
	ds_read_b128 v[52:55], v153 offset:3072
	s_waitcnt lgkmcnt(0)
	v_pk_fma_f32 v[48:49], v[48:49], v[68:69], v[52:53]
	v_cvt_pk_bf16_f32 v52, v64, v65
	v_cvt_pk_bf16_f32 v53, v60, v61
	global_store_dwordx2 v[46:47], v[52:53], off
	v_cvt_pk_bf16_f32 v52, v62, v63
	v_cvt_pk_bf16_f32 v53, v56, v57
	v_pk_fma_f32 v[50:51], v[50:51], v[70:71], v[54:55]
	global_store_dwordx2 v[46:47], v[52:53], off offset:512
	v_cvt_pk_bf16_f32 v52, v58, v59
	v_cvt_pk_bf16_f32 v53, v66, v67
	global_store_dwordx2 v[46:47], v[52:53], off offset:1024
	v_cvt_pk_bf16_f32 v48, v48, v49
	v_cvt_pk_bf16_f32 v49, v50, v51
	global_store_dwordx2 v[46:47], v[48:49], off offset:1536
	s_waitcnt vmcnt(39)
	v_lshlrev_b32_e32 v46, 16, v44
	v_and_b32_e32 v47, 0xffff0000, v44
	s_waitcnt vmcnt(38)
; #define LAS __attribute__((address_space(3)))
; __device__ __forceinline__ float bf_lo(unsigned u) { return __uint_as_float(u << 16); }
; __device__ __forceinline__ float bf_hi(unsigned u) { return __uint_as_float(u & 0xffff0000u); }
; __device__ __forceinline__ void ln_affine_l(f32x4 (&v)[4], const LAS float* gL, const LAS float* bL, int lane) {
;     float s = 0.f;
; #pragma unroll
;     for (int j = 0; j < 4; ++j) s += (v[j].x + v[j].y) + (v[j].z + v[j].w);
;     const float mean = wave_sum(s) * (1.f / D_); float s2 = 0.f;
; #pragma unroll
;     for (int j = 0; j < 4; ++j) { v[j] = v[j] - mean; s2 += (v[j].x * v[j].x + v[j].y * v[j].y) + (v[j].z * v[j].z + v[j].w * v[j].w); }
;     const float rstd = 1.f / sqrtf(wave_sum(s2) * (1.f / D_) + LN_EPS_);
; #pragma unroll
;     for (int j = 0; j < 4; ++j) v[j] = v[j] * rstd * *(const LAS f32x4*)(gL + 4 * lane + 256 * j) + *(const LAS f32x4*)(bL + 4 * lane + 256 * j);
; }
; __device__ __forceinline__ void ln1_router_tile(KArgs A, int l, int tile, int lane, const LAS bf16_t* wH) {
;     ...
;         for (int i = 0; i < 8; ++i) { f32x4 hv[4];
; #pragma unroll
;             for (int j = 0; j < 4; ++j) { hv[j].x = bf_lo(hr[i][j].x) * ALPHA_ + bf_lo(mm[i][j].x); hv[j].y = bf_hi(hr[i][j].x) * ALPHA_ + bf_hi(mm[i][j].x); hv[j].z = bf_lo(hr[i][j].y) * ALPHA_ + bf_lo(mm[i][j].y); hv[j].w = bf_hi(hr[i][j].y) * ALPHA_ + bf_hi(mm[i][j].y); }
;             ln_affine_l(hv, gL, bL, lane); store_row_bf16(HB + (size_t)(r0 + i) * D_, hv, lane); }
	v_lshlrev_b32_e32 v48, 16, v42
	v_and_b32_e32 v49, 0xffff0000, v42
	v_lshlrev_b32_e32 v44, 16, v45
	v_and_b32_e32 v45, 0xffff0000, v45
	v_lshlrev_b32_e32 v42, 16, v43
	v_and_b32_e32 v43, 0xffff0000, v43
	v_pk_fma_f32 v[46:47], v[46:47], s[78:79], v[48:49] op_sel_hi:[1,0,1]
	v_pk_fma_f32 v[42:43], v[44:45], s[78:79], v[42:43] op_sel_hi:[1,0,1]
	s_waitcnt vmcnt(37)
	v_lshlrev_b32_e32 v44, 16, v40
	v_and_b32_e32 v45, 0xffff0000, v40
	s_waitcnt vmcnt(36)
	v_lshlrev_b32_e32 v48, 16, v38
	v_and_b32_e32 v49, 0xffff0000, v38
	v_lshlrev_b32_e32 v40, 16, v41
	v_and_b32_e32 v41, 0xffff0000, v41
	v_lshlrev_b32_e32 v38, 16, v39
	v_and_b32_e32 v39, 0xffff0000, v39
	v_pk_fma_f32 v[44:45], v[44:45], s[78:79], v[48:49] op_sel_hi:[1,0,1]
	v_pk_fma_f32 v[38:39], v[40:41], s[78:79], v[38:39] op_sel_hi:[1,0,1]
	s_waitcnt vmcnt(35)
	v_lshlrev_b32_e32 v40, 16, v36
	v_and_b32_e32 v41, 0xffff0000, v36
	s_waitcnt vmcnt(34)
	v_lshlrev_b32_e32 v48, 16, v34
	v_and_b32_e32 v49, 0xffff0000, v34
	v_lshlrev_b32_e32 v36, 16, v37
	v_and_b32_e32 v37, 0xffff0000, v37
	v_lshlrev_b32_e32 v34, 16, v35
	v_and_b32_e32 v35, 0xffff0000, v35
	v_pk_fma_f32 v[40:41], v[40:41], s[78:79], v[48:49] op_sel_hi:[1,0,1]
	v_pk_fma_f32 v[48:49], v[36:37], s[78:79], v[34:35] op_sel_hi:[1,0,1]
	s_waitcnt vmcnt(33)
	v_lshlrev_b32_e32 v34, 16, v32
	v_and_b32_e32 v35, 0xffff0000, v32
	s_waitcnt vmcnt(32)
	v_lshlrev_b32_e32 v36, 16, v30
	v_and_b32_e32 v37, 0xffff0000, v30
	v_lshlrev_b32_e32 v32, 16, v33
	v_and_b32_e32 v33, 0xffff0000, v33
	v_lshlrev_b32_e32 v30, 16, v31
	v_and_b32_e32 v31, 0xffff0000, v31
	v_pk_fma_f32 v[52:53], v[32:33], s[78:79], v[30:31] op_sel_hi:[1,0,1]
	v_mov_b32_e32 v30, v46
	v_mov_b32_e32 v31, v42
	v_mov_b32_e32 v32, v47
	v_mov_b32_e32 v33, v43
	v_pk_fma_f32 v[50:51], v[34:35], s[78:79], v[36:37] op_sel_hi:[1,0,1]
	v_pk_add_f32 v[30:31], v[30:31], v[32:33]
	v_mov_b32_e32 v32, v44
	v_mov_b32_e32 v33, v38
	v_mov_b32_e32 v34, v45
	v_mov_b32_e32 v35, v39
	v_pk_add_f32 v[32:33], v[32:33], v[34:35]
	v_add_f32_e32 v9, v30, v31
	v_pk_add_f32 v[32:33], v[32:33], v[32:33] op_sel:[0,1] op_sel_hi:[1,0]
	v_pk_add_f32 v[34:35], v[40:41], v[40:41] op_sel:[0,1] op_sel_hi:[1,0]
	v_pk_add_f32 v[36:37], v[48:49], v[48:49] op_sel:[0,1] op_sel_hi:[1,0]
	v_add_f32_e32 v30, 0, v9
	v_mov_b32_e32 v31, v50
	v_mov_b32_e32 v33, v51
	v_mov_b32_e32 v35, v52
	v_mov_b32_e32 v37, v53
	v_pk_add_f32 v[30:31], v[30:31], v[32:33]
	v_pk_add_f32 v[32:33], v[34:35], v[36:37]
	s_nop 0
	v_pk_add_f32 v[30:31], v[30:31], v[32:33]
	s_nop 0
	v_add_f32_e32 v9, v30, v31
	s_waitcnt lgkmcnt(0)
	s_nop 1
	v_add_f32_dpp v9, v9, v9 quad_perm:[1,0,3,2] row_mask:0xf bank_mask:0xf
	s_waitcnt lgkmcnt(0)
	s_nop 1
	v_add_f32_dpp v9, v9, v9 quad_perm:[2,3,0,1] row_mask:0xf bank_mask:0xf
	s_waitcnt lgkmcnt(0)
	s_nop 1
	v_add_f32_dpp v9, v9, v9 row_half_mirror row_mask:0xf bank_mask:0xf
	s_waitcnt lgkmcnt(0)
	s_nop 1
	v_add_f32_dpp v9, v9, v9 row_mirror row_mask:0xf bank_mask:0xf
	s_waitcnt lgkmcnt(0)
	v_mov_b32_e32 v30, v9
	s_nop 1
	v_permlane16_swap_b32 v9, v30
	v_add_f32_e32 v9, v9, v30
	s_waitcnt lgkmcnt(0)
	v_mov_b32_e32 v30, v9
	s_nop 1
	v_permlane32_swap_b32 v9, v30
	v_add_f32_e32 v9, v9, v30
	v_fmamk_f32 v47, v9, 0xba800000, v47
	v_fmac_f32_e32 v46, 0xba800000, v9
	v_fmamk_f32 v43, v9, 0xba800000, v43
	v_fmac_f32_e32 v42, 0xba800000, v9
	v_pk_mul_f32 v[30:31], v[42:43], v[42:43]
	v_pk_mul_f32 v[32:33], v[46:47], v[46:47]
	v_fmamk_f32 v45, v9, 0xba800000, v45
	v_pk_mov_b32 v[34:35], v[32:33], v[30:31] op_sel:[1,0]
	v_mov_b32_e32 v33, v31
	v_pk_add_f32 v[30:31], v[34:35], v[32:33]
	v_fmac_f32_e32 v44, 0xba800000, v9
	v_fmamk_f32 v39, v9, 0xba800000, v39
	v_fmac_f32_e32 v38, 0xba800000, v9
	v_pk_add_f32 v[30:31], v[30:31], v[30:31] op_sel_hi:[0,1]
	v_pk_mul_f32 v[32:33], v[38:39], v[38:39]
	v_pk_mul_f32 v[34:35], v[44:45], v[44:45]
	v_fmac_f32_e32 v40, 0xba800000, v9
	v_pk_mov_b32 v[36:37], v[34:35], v[32:33] op_sel:[1,0]
	v_mov_b32_e32 v35, v33
	v_fmamk_f32 v41, v9, 0xba800000, v41
	v_fmac_f32_e32 v48, 0xba800000, v9
	v_mul_f32_e32 v30, v40, v40
	v_pk_add_f32 v[32:33], v[36:37], v[34:35]
	v_fmamk_f32 v49, v9, 0xba800000, v49
	v_pk_fma_f32 v[34:35], v[40:41], v[40:41], v[30:31] op_sel_hi:[1,1,0]
	v_mul_f32_e32 v30, v48, v48
	v_pk_add_f32 v[32:33], v[32:33], v[32:33] op_sel_hi:[0,1]
	v_pk_fma_f32 v[36:37], v[48:49], v[48:49], v[30:31] op_sel_hi:[1,1,0]
	v_fmamk_f32 v53, v9, 0xba800000, v53
	v_fmac_f32_e32 v52, 0xba800000, v9
	v_fmamk_f32 v51, v9, 0xba800000, v51
	v_fmac_f32_e32 v50, 0xba800000, v9
	v_mul_f32_e32 v34, v50, v50
	v_mul_f32_e32 v36, v51, v51
	v_mul_f32_e32 v30, v52, v52
	v_mul_f32_e32 v32, v53, v53
	v_pk_add_f32 v[34:35], v[34:35], v[36:37]
	v_pk_add_f32 v[30:31], v[30:31], v[32:33]
	s_nop 0
	v_pk_add_f32 v[30:31], v[34:35], v[30:31]
	s_nop 0
	v_add_f32_e32 v9, v30, v31
	s_waitcnt lgkmcnt(0)
	s_nop 1
	v_add_f32_dpp v9, v9, v9 quad_perm:[1,0,3,2] row_mask:0xf bank_mask:0xf
	s_waitcnt lgkmcnt(0)
	s_nop 1
	v_add_f32_dpp v9, v9, v9 quad_perm:[2,3,0,1] row_mask:0xf bank_mask:0xf
	s_waitcnt lgkmcnt(0)
	s_nop 1
	v_add_f32_dpp v9, v9, v9 row_half_mirror row_mask:0xf bank_mask:0xf
	s_waitcnt lgkmcnt(0)
	s_nop 1
	v_add_f32_dpp v9, v9, v9 row_mirror row_mask:0xf bank_mask:0xf
	s_waitcnt lgkmcnt(0)
	v_mov_b32_e32 v30, v9
	s_nop 1
	v_permlane16_swap_b32 v9, v30
	v_add_f32_e32 v9, v9, v30
	s_waitcnt lgkmcnt(0)
; #define LAS __attribute__((address_space(3)))
; __device__ __forceinline__ float bf_lo(unsigned u) { return __uint_as_float(u << 16); }
; __device__ __forceinline__ float bf_hi(unsigned u) { return __uint_as_float(u & 0xffff0000u); }
; __device__ __forceinline__ void ln_affine_l(f32x4 (&v)[4], const LAS float* gL, const LAS float* bL, int lane) {
;     float s = 0.f;
; #pragma unroll
;     for (int j = 0; j < 4; ++j) s += (v[j].x + v[j].y) + (v[j].z + v[j].w);
;     const float mean = wave_sum(s) * (1.f / D_); float s2 = 0.f;
; #pragma unroll
;     for (int j = 0; j < 4; ++j) { v[j] = v[j] - mean; s2 += (v[j].x * v[j].x + v[j].y * v[j].y) + (v[j].z * v[j].z + v[j].w * v[j].w); }
;     const float rstd = 1.f / sqrtf(wave_sum(s2) * (1.f / D_) + LN_EPS_);
; #pragma unroll
;     for (int j = 0; j < 4; ++j) v[j] = v[j] * rstd * *(const LAS f32x4*)(gL + 4 * lane + 256 * j) + *(const LAS f32x4*)(bL + 4 * lane + 256 * j);
; }
; __device__ __forceinline__ void ln1_router_tile(KArgs A, int l, int tile, int lane, const LAS bf16_t* wH) {
;     ...
;         for (int i = 0; i < 8; ++i) { f32x4 hv[4];
; #pragma unroll
;             for (int j = 0; j < 4; ++j) { hv[j].x = bf_lo(hr[i][j].x) * ALPHA_ + bf_lo(mm[i][j].x); hv[j].y = bf_hi(hr[i][j].x) * ALPHA_ + bf_hi(mm[i][j].x); hv[j].z = bf_lo(hr[i][j].y) * ALPHA_ + bf_lo(mm[i][j].y); hv[j].w = bf_hi(hr[i][j].y) * ALPHA_ + bf_hi(mm[i][j].y); }
;             ln_affine_l(hv, gL, bL, lane); store_row_bf16(HB + (size_t)(r0 + i) * D_, hv, lane); }
	v_mov_b32_e32 v30, v9
	s_nop 1
	v_permlane32_swap_b32 v9, v30
	v_add_f32_e32 v9, v9, v30
	v_fmamk_f32 v9, v9, 0x3a800000, v227
	v_cmp_gt_f32_e32 vcc, s47, v9
	v_mul_f32_e32 v30, 0x4f800000, v9
	s_nop 0
	v_cndmask_b32_e32 v9, v9, v30, vcc
	v_sqrt_f32_e32 v30, v9
	s_nop 0
	v_add_u32_e32 v31, -1, v30
	v_fma_f32 v32, -v31, v30, v9
	v_cmp_ge_f32_e64 s[8:9], 0, v32
	v_add_u32_e32 v32, 1, v30
	s_nop 0
	v_cndmask_b32_e64 v31, v30, v31, s[8:9]
	v_fma_f32 v30, -v32, v30, v9
	v_cmp_lt_f32_e64 s[8:9], 0, v30
	s_nop 1
	v_cndmask_b32_e64 v30, v31, v32, s[8:9]
	v_mul_f32_e32 v31, 0x37800000, v30
	v_cndmask_b32_e32 v30, v30, v31, vcc
	v_cmp_class_f32_e32 vcc, v9, v228
	s_nop 1
	v_cndmask_b32_e32 v9, v30, v9, vcc
	v_div_scale_f32 v30, s[0:1], v9, v9, 1.0
	v_rcp_f32_e32 v31, v30
	s_nop 0
	v_fma_f32 v32, -v30, v31, 1.0
	v_fmac_f32_e32 v31, v32, v31
	v_div_scale_f32 v32, vcc, 1.0, v9, 1.0
	v_mul_f32_e32 v33, v32, v31
	v_fma_f32 v34, -v30, v33, v32
	v_fmac_f32_e32 v33, v34, v31
	v_fma_f32 v30, -v30, v33, v32
	v_div_fmas_f32 v30, v30, v31, v33
	v_div_fixup_f32 v54, v30, v9, 1.0
	ds_read_b128 v[30:33], v152
	ds_read_b128 v[34:37], v153
	v_pk_mul_f32 v[46:47], v[46:47], v[54:55] op_sel_hi:[1,0]
	v_pk_mul_f32 v[42:43], v[42:43], v[54:55] op_sel_hi:[1,0]
	v_pk_mul_f32 v[44:45], v[44:45], v[54:55] op_sel_hi:[1,0]
	v_pk_mul_f32 v[38:39], v[38:39], v[54:55] op_sel_hi:[1,0]
	s_waitcnt lgkmcnt(0)
	v_pk_fma_f32 v[42:43], v[32:33], v[42:43], v[36:37]
	v_pk_fma_f32 v[46:47], v[30:31], v[46:47], v[34:35]
	ds_read_b128 v[30:33], v152 offset:1024
	ds_read_b128 v[34:37], v153 offset:1024
	v_pk_mul_f32 v[40:41], v[40:41], v[54:55] op_sel_hi:[1,0]
	v_pk_mul_f32 v[48:49], v[48:49], v[54:55] op_sel_hi:[1,0]
	v_pk_mul_f32 v[50:51], v[50:51], v[54:55] op_sel_hi:[1,0]
	v_pk_mul_f32 v[52:53], v[52:53], v[54:55] op_sel_hi:[1,0]
	s_waitcnt lgkmcnt(0)
	v_pk_fma_f32 v[38:39], v[32:33], v[38:39], v[36:37]
	v_pk_fma_f32 v[44:45], v[30:31], v[44:45], v[34:35]
	ds_read_b128 v[30:33], v152 offset:2048
	ds_read_b128 v[34:37], v153 offset:2048
	s_waitcnt lgkmcnt(0)
	v_pk_fma_f32 v[48:49], v[32:33], v[48:49], v[36:37]
	v_pk_fma_f32 v[40:41], v[30:31], v[40:41], v[34:35]
	ds_read_b128 v[30:33], v152 offset:3072
	ds_read_b128 v[34:37], v153 offset:3072
	s_waitcnt lgkmcnt(0)
	v_pk_fma_f32 v[30:31], v[30:31], v[50:51], v[34:35]
	v_cvt_pk_bf16_f32 v34, v46, v47
	v_cvt_pk_bf16_f32 v35, v42, v43
	global_store_dwordx2 v[28:29], v[34:35], off
	v_cvt_pk_bf16_f32 v34, v44, v45
	v_cvt_pk_bf16_f32 v35, v38, v39
	v_pk_fma_f32 v[32:33], v[32:33], v[52:53], v[36:37]
	global_store_dwordx2 v[28:29], v[34:35], off offset:512
	v_cvt_pk_bf16_f32 v34, v40, v41
	v_cvt_pk_bf16_f32 v35, v48, v49
	global_store_dwordx2 v[28:29], v[34:35], off offset:1024
	v_cvt_pk_bf16_f32 v30, v30, v31
	v_cvt_pk_bf16_f32 v31, v32, v33
	global_store_dwordx2 v[28:29], v[30:31], off offset:1536
	s_waitcnt vmcnt(35)
	v_lshlrev_b32_e32 v28, 16, v26
	v_and_b32_e32 v29, 0xffff0000, v26
	s_waitcnt vmcnt(34)
	v_lshlrev_b32_e32 v30, 16, v24
	v_and_b32_e32 v31, 0xffff0000, v24
	v_lshlrev_b32_e32 v26, 16, v27
	v_and_b32_e32 v27, 0xffff0000, v27
	v_lshlrev_b32_e32 v24, 16, v25
	v_and_b32_e32 v25, 0xffff0000, v25
	v_pk_fma_f32 v[28:29], v[28:29], s[78:79], v[30:31] op_sel_hi:[1,0,1]
	v_pk_fma_f32 v[24:25], v[26:27], s[78:79], v[24:25] op_sel_hi:[1,0,1]
	s_waitcnt vmcnt(33)
	v_lshlrev_b32_e32 v26, 16, v22
	v_and_b32_e32 v27, 0xffff0000, v22
	s_waitcnt vmcnt(32)
	v_lshlrev_b32_e32 v30, 16, v20
	v_and_b32_e32 v31, 0xffff0000, v20
	v_lshlrev_b32_e32 v22, 16, v23
	v_and_b32_e32 v23, 0xffff0000, v23
	v_lshlrev_b32_e32 v20, 16, v21
	v_and_b32_e32 v21, 0xffff0000, v21
	v_pk_fma_f32 v[26:27], v[26:27], s[78:79], v[30:31] op_sel_hi:[1,0,1]
	v_pk_fma_f32 v[20:21], v[22:23], s[78:79], v[20:21] op_sel_hi:[1,0,1]
	s_waitcnt vmcnt(31)
	v_lshlrev_b32_e32 v22, 16, v18
	v_and_b32_e32 v23, 0xffff0000, v18
	s_waitcnt vmcnt(30)
	v_lshlrev_b32_e32 v30, 16, v16
	v_and_b32_e32 v31, 0xffff0000, v16
	v_lshlrev_b32_e32 v18, 16, v19
	v_and_b32_e32 v19, 0xffff0000, v19
	v_lshlrev_b32_e32 v16, 16, v17
	v_and_b32_e32 v17, 0xffff0000, v17
	v_pk_fma_f32 v[22:23], v[22:23], s[78:79], v[30:31] op_sel_hi:[1,0,1]
	v_pk_fma_f32 v[30:31], v[18:19], s[78:79], v[16:17] op_sel_hi:[1,0,1]
	s_waitcnt vmcnt(29)
	v_lshlrev_b32_e32 v16, 16, v14
	v_and_b32_e32 v17, 0xffff0000, v14
	s_waitcnt vmcnt(28)
	v_lshlrev_b32_e32 v18, 16, v12
	v_and_b32_e32 v19, 0xffff0000, v12
	v_lshlrev_b32_e32 v14, 16, v15
	v_and_b32_e32 v15, 0xffff0000, v15
	v_lshlrev_b32_e32 v12, 16, v13
	v_and_b32_e32 v13, 0xffff0000, v13
	v_pk_fma_f32 v[34:35], v[14:15], s[78:79], v[12:13] op_sel_hi:[1,0,1]
	v_mov_b32_e32 v12, v28
	v_mov_b32_e32 v13, v24
	v_mov_b32_e32 v14, v29
	v_mov_b32_e32 v15, v25
	v_pk_fma_f32 v[32:33], v[16:17], s[78:79], v[18:19] op_sel_hi:[1,0,1]
	v_pk_add_f32 v[12:13], v[12:13], v[14:15]
	v_mov_b32_e32 v14, v26
	v_mov_b32_e32 v15, v20
	v_mov_b32_e32 v16, v27
	v_mov_b32_e32 v17, v21
	v_pk_add_f32 v[14:15], v[14:15], v[16:17]
	v_add_f32_e32 v9, v12, v13
	v_pk_add_f32 v[14:15], v[14:15], v[14:15] op_sel:[0,1] op_sel_hi:[1,0]
	v_pk_add_f32 v[16:17], v[22:23], v[22:23] op_sel:[0,1] op_sel_hi:[1,0]
	v_pk_add_f32 v[18:19], v[30:31], v[30:31] op_sel:[0,1] op_sel_hi:[1,0]
	v_add_f32_e32 v12, 0, v9
	v_mov_b32_e32 v13, v32
	v_mov_b32_e32 v15, v33
	v_mov_b32_e32 v17, v34
	v_mov_b32_e32 v19, v35
	v_pk_add_f32 v[12:13], v[12:13], v[14:15]
	v_pk_add_f32 v[14:15], v[16:17], v[18:19]
	s_nop 0
	v_pk_add_f32 v[12:13], v[12:13], v[14:15]
	s_nop 0
	v_add_f32_e32 v9, v12, v13
	s_waitcnt lgkmcnt(0)
	s_nop 1
	v_add_f32_dpp v9, v9, v9 quad_perm:[1,0,3,2] row_mask:0xf bank_mask:0xf
	s_waitcnt lgkmcnt(0)
; #define LAS __attribute__((address_space(3)))
; __device__ __forceinline__ float bf_lo(unsigned u) { return __uint_as_float(u << 16); }
; __device__ __forceinline__ float bf_hi(unsigned u) { return __uint_as_float(u & 0xffff0000u); }
; __device__ __forceinline__ void ln_affine_l(f32x4 (&v)[4], const LAS float* gL, const LAS float* bL, int lane) {
;     float s = 0.f;
; #pragma unroll
;     for (int j = 0; j < 4; ++j) s += (v[j].x + v[j].y) + (v[j].z + v[j].w);
;     const float mean = wave_sum(s) * (1.f / D_); float s2 = 0.f;
; #pragma unroll
;     for (int j = 0; j < 4; ++j) { v[j] = v[j] - mean; s2 += (v[j].x * v[j].x + v[j].y * v[j].y) + (v[j].z * v[j].z + v[j].w * v[j].w); }
;     const float rstd = 1.f / sqrtf(wave_sum(s2) * (1.f / D_) + LN_EPS_);
; #pragma unroll
;     for (int j = 0; j < 4; ++j) v[j] = v[j] * rstd * *(const LAS f32x4*)(gL + 4 * lane + 256 * j) + *(const LAS f32x4*)(bL + 4 * lane + 256 * j);
; }
; __device__ __forceinline__ void ln1_router_tile(KArgs A, int l, int tile, int lane, const LAS bf16_t* wH) {
;     ...
;         for (int i = 0; i < 8; ++i) { f32x4 hv[4];
; #pragma unroll
;             for (int j = 0; j < 4; ++j) { hv[j].x = bf_lo(hr[i][j].x) * ALPHA_ + bf_lo(mm[i][j].x); hv[j].y = bf_hi(hr[i][j].x) * ALPHA_ + bf_hi(mm[i][j].x); hv[j].z = bf_lo(hr[i][j].y) * ALPHA_ + bf_lo(mm[i][j].y); hv[j].w = bf_hi(hr[i][j].y) * ALPHA_ + bf_hi(mm[i][j].y); }
;             ln_affine_l(hv, gL, bL, lane); store_row_bf16(HB + (size_t)(r0 + i) * D_, hv, lane); }
	s_nop 1
	v_add_f32_dpp v9, v9, v9 quad_perm:[2,3,0,1] row_mask:0xf bank_mask:0xf
	s_waitcnt lgkmcnt(0)
	s_nop 1
	v_add_f32_dpp v9, v9, v9 row_half_mirror row_mask:0xf bank_mask:0xf
	s_waitcnt lgkmcnt(0)
	s_nop 1
	v_add_f32_dpp v9, v9, v9 row_mirror row_mask:0xf bank_mask:0xf
	s_waitcnt lgkmcnt(0)
	v_mov_b32_e32 v12, v9
	s_nop 1
	v_permlane16_swap_b32 v9, v12
	v_add_f32_e32 v9, v9, v12
	s_waitcnt lgkmcnt(0)
	v_mov_b32_e32 v12, v9
	s_nop 1
	v_permlane32_swap_b32 v9, v12
	v_add_f32_e32 v9, v9, v12
	v_fmamk_f32 v29, v9, 0xba800000, v29
	v_fmac_f32_e32 v28, 0xba800000, v9
	v_fmamk_f32 v25, v9, 0xba800000, v25
	v_fmac_f32_e32 v24, 0xba800000, v9
	v_pk_mul_f32 v[12:13], v[24:25], v[24:25]
	v_pk_mul_f32 v[14:15], v[28:29], v[28:29]
	v_fmamk_f32 v27, v9, 0xba800000, v27
	v_pk_mov_b32 v[16:17], v[14:15], v[12:13] op_sel:[1,0]
	v_mov_b32_e32 v15, v13
	v_pk_add_f32 v[12:13], v[16:17], v[14:15]
	v_fmac_f32_e32 v26, 0xba800000, v9
	v_fmamk_f32 v21, v9, 0xba800000, v21
	v_fmac_f32_e32 v20, 0xba800000, v9
	v_pk_add_f32 v[12:13], v[12:13], v[12:13] op_sel_hi:[0,1]
	v_pk_mul_f32 v[14:15], v[20:21], v[20:21]
	v_pk_mul_f32 v[16:17], v[26:27], v[26:27]
	v_fmac_f32_e32 v22, 0xba800000, v9
	v_pk_mov_b32 v[18:19], v[16:17], v[14:15] op_sel:[1,0]
	v_mov_b32_e32 v17, v15
	v_fmamk_f32 v23, v9, 0xba800000, v23
	v_fmac_f32_e32 v30, 0xba800000, v9
	v_mul_f32_e32 v12, v22, v22
	v_pk_add_f32 v[14:15], v[18:19], v[16:17]
	v_fmamk_f32 v31, v9, 0xba800000, v31
	v_pk_fma_f32 v[16:17], v[22:23], v[22:23], v[12:13] op_sel_hi:[1,1,0]
	v_mul_f32_e32 v12, v30, v30
	v_pk_add_f32 v[14:15], v[14:15], v[14:15] op_sel_hi:[0,1]
	v_pk_fma_f32 v[18:19], v[30:31], v[30:31], v[12:13] op_sel_hi:[1,1,0]
	v_fmamk_f32 v35, v9, 0xba800000, v35
	v_fmac_f32_e32 v34, 0xba800000, v9
	v_fmamk_f32 v33, v9, 0xba800000, v33
	v_fmac_f32_e32 v32, 0xba800000, v9
	v_mul_f32_e32 v16, v32, v32
	v_mul_f32_e32 v18, v33, v33
	v_mul_f32_e32 v12, v34, v34
	v_mul_f32_e32 v14, v35, v35
	v_pk_add_f32 v[16:17], v[16:17], v[18:19]
	v_pk_add_f32 v[12:13], v[12:13], v[14:15]
	s_nop 0
	v_pk_add_f32 v[12:13], v[16:17], v[12:13]
	s_nop 0
	v_add_f32_e32 v9, v12, v13
	s_waitcnt lgkmcnt(0)
	s_nop 1
	v_add_f32_dpp v9, v9, v9 quad_perm:[1,0,3,2] row_mask:0xf bank_mask:0xf
	s_waitcnt lgkmcnt(0)
	s_nop 1
	v_add_f32_dpp v9, v9, v9 quad_perm:[2,3,0,1] row_mask:0xf bank_mask:0xf
	s_waitcnt lgkmcnt(0)
	s_nop 1
	v_add_f32_dpp v9, v9, v9 row_half_mirror row_mask:0xf bank_mask:0xf
	s_waitcnt lgkmcnt(0)
	s_nop 1
	v_add_f32_dpp v9, v9, v9 row_mirror row_mask:0xf bank_mask:0xf
	s_waitcnt lgkmcnt(0)
	v_mov_b32_e32 v12, v9
	s_nop 1
	v_permlane16_swap_b32 v9, v12
	v_add_f32_e32 v9, v9, v12
	s_waitcnt lgkmcnt(0)
	v_mov_b32_e32 v12, v9
	s_nop 1
	v_permlane32_swap_b32 v9, v12
	v_add_f32_e32 v9, v9, v12
	v_fmamk_f32 v9, v9, 0x3a800000, v227
	v_cmp_gt_f32_e32 vcc, s47, v9
	v_mul_f32_e32 v12, 0x4f800000, v9
	s_nop 0
	v_cndmask_b32_e32 v9, v9, v12, vcc
	v_sqrt_f32_e32 v12, v9
	s_nop 0
	v_add_u32_e32 v13, -1, v12
	v_fma_f32 v14, -v13, v12, v9
	v_cmp_ge_f32_e64 s[8:9], 0, v14
	v_add_u32_e32 v14, 1, v12
	s_nop 0
	v_cndmask_b32_e64 v13, v12, v13, s[8:9]
	v_fma_f32 v12, -v14, v12, v9
	v_cmp_lt_f32_e64 s[8:9], 0, v12
	s_nop 1
	v_cndmask_b32_e64 v12, v13, v14, s[8:9]
	v_mul_f32_e32 v13, 0x37800000, v12
	v_cndmask_b32_e32 v12, v12, v13, vcc
	v_cmp_class_f32_e32 vcc, v9, v228
	s_mov_b64 s[8:9], 0
	s_nop 0
	v_cndmask_b32_e32 v9, v12, v9, vcc
	v_div_scale_f32 v12, s[0:1], v9, v9, 1.0
	v_rcp_f32_e32 v13, v12
	s_nop 0
	v_fma_f32 v14, -v12, v13, 1.0
	v_fmac_f32_e32 v13, v14, v13
	v_div_scale_f32 v14, vcc, 1.0, v9, 1.0
	v_mul_f32_e32 v15, v14, v13
	v_fma_f32 v16, -v12, v15, v14
	v_fmac_f32_e32 v15, v16, v13
	v_fma_f32 v12, -v12, v15, v14
	v_div_fmas_f32 v12, v12, v13, v15
	v_div_fixup_f32 v36, v12, v9, 1.0
	ds_read_b128 v[12:15], v152
	ds_read_b128 v[16:19], v153
	v_pk_mul_f32 v[28:29], v[28:29], v[36:37] op_sel_hi:[1,0]
	v_pk_mul_f32 v[24:25], v[24:25], v[36:37] op_sel_hi:[1,0]
	v_pk_mul_f32 v[26:27], v[26:27], v[36:37] op_sel_hi:[1,0]
	v_pk_mul_f32 v[20:21], v[20:21], v[36:37] op_sel_hi:[1,0]
	s_waitcnt lgkmcnt(0)
	v_pk_fma_f32 v[24:25], v[14:15], v[24:25], v[18:19]
	v_pk_fma_f32 v[28:29], v[12:13], v[28:29], v[16:17]
	ds_read_b128 v[12:15], v152 offset:1024
	ds_read_b128 v[16:19], v153 offset:1024
	v_pk_mul_f32 v[22:23], v[22:23], v[36:37] op_sel_hi:[1,0]
	v_pk_mul_f32 v[30:31], v[30:31], v[36:37] op_sel_hi:[1,0]
	v_pk_mul_f32 v[32:33], v[32:33], v[36:37] op_sel_hi:[1,0]
	v_pk_mul_f32 v[34:35], v[34:35], v[36:37] op_sel_hi:[1,0]
	s_waitcnt lgkmcnt(0)
	v_pk_fma_f32 v[20:21], v[14:15], v[20:21], v[18:19]
	v_pk_fma_f32 v[26:27], v[12:13], v[26:27], v[16:17]
	ds_read_b128 v[12:15], v152 offset:2048
	ds_read_b128 v[16:19], v153 offset:2048
	s_and_b64 vcc, exec, s[6:7]
	s_waitcnt lgkmcnt(0)
	v_pk_fma_f32 v[30:31], v[14:15], v[30:31], v[18:19]
	v_pk_fma_f32 v[22:23], v[12:13], v[22:23], v[16:17]
	ds_read_b128 v[12:15], v152 offset:3072
	ds_read_b128 v[16:19], v153 offset:3072
	s_waitcnt lgkmcnt(0)
	v_pk_fma_f32 v[12:13], v[12:13], v[32:33], v[16:17]
	v_cvt_pk_bf16_f32 v16, v28, v29
	v_cvt_pk_bf16_f32 v17, v24, v25
	global_store_dwordx2 v[10:11], v[16:17], off
	v_cvt_pk_bf16_f32 v16, v26, v27
	v_cvt_pk_bf16_f32 v17, v20, v21
	v_pk_fma_f32 v[14:15], v[14:15], v[34:35], v[18:19]
	global_store_dwordx2 v[10:11], v[16:17], off offset:512
	v_cvt_pk_bf16_f32 v16, v22, v23
	v_cvt_pk_bf16_f32 v17, v30, v31
	global_store_dwordx2 v[10:11], v[16:17], off offset:1024
	v_cvt_pk_bf16_f32 v12, v12, v13
	v_cvt_pk_bf16_f32 v13, v14, v15
	global_store_dwordx2 v[10:11], v[12:13], off offset:1536
	s_cbranch_vccz .LBB0_584
; #define LAS __attribute__((address_space(3)))
; __device__ __forceinline__ void ln1_router_tile(KArgs A, int l, int tile, int lane, const LAS bf16_t* wH) {
;     ...
;     asm volatile("s_waitcnt vmcnt(0)" ::: "memory");
;     const bf16_t* hb = HB + (size_t)(lane & 15) * D_ + 8 * (lane >> 4);
;     const LAS bf16_t* wb = wH + (lane & 15) * RW_LD + 8 * (lane >> 4);
;     f32x4 acc = (f32x4){0.f, 0.f, 0.f, 0.f};
; #pragma unroll 8
;     for (int ks = 0; ks < 32; ++ks) {
;         const bf16x8 a = __builtin_bit_cast(bf16x8, *(const u32x4*)(hb + 32 * ks));
;         const bf16x8 bh = *(const LAS bf16x8*)(wb + 32 * ks), bl = *(const LAS bf16x8*)(wb + NE * RW_LD + 32 * ks);
;         acc = __builtin_amdgcn_mfma_f32_16x16x32_bf16(a, bh, acc, 0, 0, 0); acc = __builtin_amdgcn_mfma_f32_16x16x32_bf16(a, bl, acc, 0, 0, 0);
;     }
	s_ashr_i32 s13, s12, 31
	s_waitcnt vmcnt(0)
	s_lshl_b64 s[0:1], s[12:13], 11
	v_mov_b32_e32 v0, 0
	v_lshl_add_u64 v[10:11], v[6:7], 0, s[0:1]
	s_mov_b32 s0, 0
	v_mov_b32_e32 v1, v0
	v_mov_b32_e32 v2, v0
	v_mov_b32_e32 v3, v0
	global_load_dwordx4 v[24:27], v[10:11], off offset:-256
	global_load_dwordx4 v[28:31], v[10:11], off offset:-192
	global_load_dwordx4 v[32:35], v[10:11], off offset:-128
	global_load_dwordx4 v[36:39], v[10:11], off offset:-64
	global_load_dwordx4 v[40:43], v[10:11], off
	global_load_dwordx4 v[44:47], v[10:11], off offset:64
	global_load_dwordx4 v[48:51], v[10:11], off offset:128
	global_load_dwordx4 v[52:55], v[10:11], off offset:192
	global_load_dwordx4 v[56:59], v[10:11], off offset:256
	global_load_dwordx4 v[60:63], v[10:11], off offset:320
	global_load_dwordx4 v[64:67], v[10:11], off offset:384
	global_load_dwordx4 v[68:71], v[10:11], off offset:448
	global_load_dwordx4 v[72:75], v[10:11], off offset:512
	global_load_dwordx4 v[76:79], v[10:11], off offset:576
	global_load_dwordx4 v[80:83], v[10:11], off offset:640
	global_load_dwordx4 v[84:87], v[10:11], off offset:704
	global_load_dwordx4 v[88:91], v[10:11], off offset:768
	global_load_dwordx4 v[92:95], v[10:11], off offset:832
	global_load_dwordx4 v[96:99], v[10:11], off offset:896
	global_load_dwordx4 v[100:103], v[10:11], off offset:960
	global_load_dwordx4 v[104:107], v[10:11], off offset:1024
	global_load_dwordx4 v[108:111], v[10:11], off offset:1088
	global_load_dwordx4 v[112:115], v[10:11], off offset:1152
	global_load_dwordx4 v[116:119], v[10:11], off offset:1216
	global_load_dwordx4 v[120:123], v[10:11], off offset:1280
	global_load_dwordx4 v[124:127], v[10:11], off offset:1344
	global_load_dwordx4 v[128:131], v[10:11], off offset:1408
	global_load_dwordx4 v[132:135], v[10:11], off offset:1472
	global_load_dwordx4 v[136:139], v[10:11], off offset:1536
	global_load_dwordx4 v[140:143], v[10:11], off offset:1600
	global_load_dwordx4 v[144:147], v[10:11], off offset:1664
	global_load_dwordx4 v[148:151], v[10:11], off offset:1728
	ds_read_b128 v[16:19], v155
	ds_read_b128 v[20:23], v155 offset:33024
	ds_read_b128 v[162:165], v155 offset:64
	ds_read_b128 v[166:169], v155 offset:33088
	s_waitcnt vmcnt(31) lgkmcnt(2)
	v_mfma_f32_16x16x32_bf16 v[0:3], v[24:27], v[16:19], v[0:3]
	v_mfma_f32_16x16x32_bf16 v[0:3], v[24:27], v[20:23], v[0:3]
	ds_read_b128 v[16:19], v155 offset:128
	ds_read_b128 v[20:23], v155 offset:33152
	s_waitcnt vmcnt(30) lgkmcnt(2)
	v_mfma_f32_16x16x32_bf16 v[0:3], v[28:31], v[162:165], v[0:3]
	v_mfma_f32_16x16x32_bf16 v[0:3], v[28:31], v[166:169], v[0:3]
	ds_read_b128 v[162:165], v155 offset:192
	ds_read_b128 v[166:169], v155 offset:33216
	s_waitcnt vmcnt(29) lgkmcnt(2)
	v_mfma_f32_16x16x32_bf16 v[0:3], v[32:35], v[16:19], v[0:3]
	v_mfma_f32_16x16x32_bf16 v[0:3], v[32:35], v[20:23], v[0:3]
	ds_read_b128 v[16:19], v155 offset:256
	ds_read_b128 v[20:23], v155 offset:33280
	s_waitcnt vmcnt(28) lgkmcnt(2)
	v_mfma_f32_16x16x32_bf16 v[0:3], v[36:39], v[162:165], v[0:3]
	v_mfma_f32_16x16x32_bf16 v[0:3], v[36:39], v[166:169], v[0:3]
	ds_read_b128 v[162:165], v155 offset:320
	ds_read_b128 v[166:169], v155 offset:33344
	s_waitcnt vmcnt(27) lgkmcnt(2)
	v_mfma_f32_16x16x32_bf16 v[0:3], v[40:43], v[16:19], v[0:3]
	v_mfma_f32_16x16x32_bf16 v[0:3], v[40:43], v[20:23], v[0:3]
	ds_read_b128 v[16:19], v155 offset:384
	ds_read_b128 v[20:23], v155 offset:33408
	s_waitcnt vmcnt(26) lgkmcnt(2)
	v_mfma_f32_16x16x32_bf16 v[0:3], v[44:47], v[162:165], v[0:3]
	v_mfma_f32_16x16x32_bf16 v[0:3], v[44:47], v[166:169], v[0:3]
	ds_read_b128 v[162:165], v155 offset:448
	ds_read_b128 v[166:169], v155 offset:33472
	s_waitcnt vmcnt(25) lgkmcnt(2)
	v_mfma_f32_16x16x32_bf16 v[0:3], v[48:51], v[16:19], v[0:3]
	v_mfma_f32_16x16x32_bf16 v[0:3], v[48:51], v[20:23], v[0:3]
	ds_read_b128 v[16:19], v155 offset:512
	ds_read_b128 v[20:23], v155 offset:33536
	s_waitcnt vmcnt(24) lgkmcnt(2)
	v_mfma_f32_16x16x32_bf16 v[0:3], v[52:55], v[162:165], v[0:3]
	v_mfma_f32_16x16x32_bf16 v[0:3], v[52:55], v[166:169], v[0:3]
	ds_read_b128 v[162:165], v155 offset:576
	ds_read_b128 v[166:169], v155 offset:33600
	s_waitcnt vmcnt(23) lgkmcnt(2)
	v_mfma_f32_16x16x32_bf16 v[0:3], v[56:59], v[16:19], v[0:3]
	v_mfma_f32_16x16x32_bf16 v[0:3], v[56:59], v[20:23], v[0:3]
	ds_read_b128 v[16:19], v155 offset:640
	ds_read_b128 v[20:23], v155 offset:33664
	s_waitcnt vmcnt(22) lgkmcnt(2)
	v_mfma_f32_16x16x32_bf16 v[0:3], v[60:63], v[162:165], v[0:3]
	v_mfma_f32_16x16x32_bf16 v[0:3], v[60:63], v[166:169], v[0:3]
	ds_read_b128 v[162:165], v155 offset:704
	ds_read_b128 v[166:169], v155 offset:33728
	s_waitcnt vmcnt(21) lgkmcnt(2)
	v_mfma_f32_16x16x32_bf16 v[0:3], v[64:67], v[16:19], v[0:3]
	v_mfma_f32_16x16x32_bf16 v[0:3], v[64:67], v[20:23], v[0:3]
	ds_read_b128 v[16:19], v155 offset:768
	ds_read_b128 v[20:23], v155 offset:33792
	s_waitcnt vmcnt(20) lgkmcnt(2)
	v_mfma_f32_16x16x32_bf16 v[0:3], v[68:71], v[162:165], v[0:3]
	v_mfma_f32_16x16x32_bf16 v[0:3], v[68:71], v[166:169], v[0:3]
	ds_read_b128 v[162:165], v155 offset:832
	ds_read_b128 v[166:169], v155 offset:33856
	s_waitcnt vmcnt(19) lgkmcnt(2)
	v_mfma_f32_16x16x32_bf16 v[0:3], v[72:75], v[16:19], v[0:3]
	v_mfma_f32_16x16x32_bf16 v[0:3], v[72:75], v[20:23], v[0:3]
	ds_read_b128 v[16:19], v155 offset:896
	ds_read_b128 v[20:23], v155 offset:33920
	s_waitcnt vmcnt(18) lgkmcnt(2)
	v_mfma_f32_16x16x32_bf16 v[0:3], v[76:79], v[162:165], v[0:3]
	v_mfma_f32_16x16x32_bf16 v[0:3], v[76:79], v[166:169], v[0:3]
	ds_read_b128 v[162:165], v155 offset:960
	ds_read_b128 v[166:169], v155 offset:33984
	s_waitcnt vmcnt(17) lgkmcnt(2)
; #define LAS __attribute__((address_space(3)))
; __device__ __forceinline__ void ln1_router_tile(KArgs A, int l, int tile, int lane, const LAS bf16_t* wH) {
;     ...
;     f32x4 acc = (f32x4){0.f, 0.f, 0.f, 0.f};
; #pragma unroll 8
;     for (int ks = 0; ks < 32; ++ks) {
;         const bf16x8 a = __builtin_bit_cast(bf16x8, *(const u32x4*)(hb + 32 * ks));
;         const bf16x8 bh = *(const LAS bf16x8*)(wb + 32 * ks), bl = *(const LAS bf16x8*)(wb + NE * RW_LD + 32 * ks);
;         acc = __builtin_amdgcn_mfma_f32_16x16x32_bf16(a, bh, acc, 0, 0, 0); acc = __builtin_amdgcn_mfma_f32_16x16x32_bf16(a, bl, acc, 0, 0, 0);
;     }
;     f32x4 p;
; #pragma unroll
;     for (int q = 0; q < 4; ++q) { float x = acc[q], mx = x;
; #pragma unroll
;         for (int o = 1; o < 16; o <<= 1) mx = fmaxf(mx, __shfl_xor(mx, o));
	v_mfma_f32_16x16x32_bf16 v[0:3], v[80:83], v[16:19], v[0:3]
	v_mfma_f32_16x16x32_bf16 v[0:3], v[80:83], v[20:23], v[0:3]
	ds_read_b128 v[16:19], v155 offset:1024
	ds_read_b128 v[20:23], v155 offset:34048
	s_waitcnt vmcnt(16) lgkmcnt(2)
	v_mfma_f32_16x16x32_bf16 v[0:3], v[84:87], v[162:165], v[0:3]
	v_mfma_f32_16x16x32_bf16 v[0:3], v[84:87], v[166:169], v[0:3]
	ds_read_b128 v[162:165], v155 offset:1088
	ds_read_b128 v[166:169], v155 offset:34112
	s_waitcnt vmcnt(15) lgkmcnt(2)
	v_mfma_f32_16x16x32_bf16 v[0:3], v[88:91], v[16:19], v[0:3]
	v_mfma_f32_16x16x32_bf16 v[0:3], v[88:91], v[20:23], v[0:3]
	ds_read_b128 v[16:19], v155 offset:1152
	ds_read_b128 v[20:23], v155 offset:34176
	s_waitcnt vmcnt(14) lgkmcnt(2)
	v_mfma_f32_16x16x32_bf16 v[0:3], v[92:95], v[162:165], v[0:3]
	v_mfma_f32_16x16x32_bf16 v[0:3], v[92:95], v[166:169], v[0:3]
	ds_read_b128 v[162:165], v155 offset:1216
	ds_read_b128 v[166:169], v155 offset:34240
	s_waitcnt vmcnt(13) lgkmcnt(2)
	v_mfma_f32_16x16x32_bf16 v[0:3], v[96:99], v[16:19], v[0:3]
	v_mfma_f32_16x16x32_bf16 v[0:3], v[96:99], v[20:23], v[0:3]
	ds_read_b128 v[16:19], v155 offset:1280
	ds_read_b128 v[20:23], v155 offset:34304
	s_waitcnt vmcnt(12) lgkmcnt(2)
	v_mfma_f32_16x16x32_bf16 v[0:3], v[100:103], v[162:165], v[0:3]
	v_mfma_f32_16x16x32_bf16 v[0:3], v[100:103], v[166:169], v[0:3]
	ds_read_b128 v[162:165], v155 offset:1344
	ds_read_b128 v[166:169], v155 offset:34368
	s_waitcnt vmcnt(11) lgkmcnt(2)
	v_mfma_f32_16x16x32_bf16 v[0:3], v[104:107], v[16:19], v[0:3]
	v_mfma_f32_16x16x32_bf16 v[0:3], v[104:107], v[20:23], v[0:3]
	ds_read_b128 v[16:19], v155 offset:1408
	ds_read_b128 v[20:23], v155 offset:34432
	s_waitcnt vmcnt(10) lgkmcnt(2)
	v_mfma_f32_16x16x32_bf16 v[0:3], v[108:111], v[162:165], v[0:3]
	v_mfma_f32_16x16x32_bf16 v[0:3], v[108:111], v[166:169], v[0:3]
	ds_read_b128 v[162:165], v155 offset:1472
	ds_read_b128 v[166:169], v155 offset:34496
	s_waitcnt vmcnt(9) lgkmcnt(2)
	v_mfma_f32_16x16x32_bf16 v[0:3], v[112:115], v[16:19], v[0:3]
	v_mfma_f32_16x16x32_bf16 v[0:3], v[112:115], v[20:23], v[0:3]
	ds_read_b128 v[16:19], v155 offset:1536
	ds_read_b128 v[20:23], v155 offset:34560
	s_waitcnt vmcnt(8) lgkmcnt(2)
	v_mfma_f32_16x16x32_bf16 v[0:3], v[116:119], v[162:165], v[0:3]
	v_mfma_f32_16x16x32_bf16 v[0:3], v[116:119], v[166:169], v[0:3]
	ds_read_b128 v[162:165], v155 offset:1600
	ds_read_b128 v[166:169], v155 offset:34624
	s_waitcnt vmcnt(7) lgkmcnt(2)
	v_mfma_f32_16x16x32_bf16 v[0:3], v[120:123], v[16:19], v[0:3]
	v_mfma_f32_16x16x32_bf16 v[0:3], v[120:123], v[20:23], v[0:3]
	ds_read_b128 v[16:19], v155 offset:1664
	ds_read_b128 v[20:23], v155 offset:34688
	s_waitcnt vmcnt(6) lgkmcnt(2)
	v_mfma_f32_16x16x32_bf16 v[0:3], v[124:127], v[162:165], v[0:3]
	v_mfma_f32_16x16x32_bf16 v[0:3], v[124:127], v[166:169], v[0:3]
	ds_read_b128 v[162:165], v155 offset:1728
	ds_read_b128 v[166:169], v155 offset:34752
	s_waitcnt vmcnt(5) lgkmcnt(2)
	v_mfma_f32_16x16x32_bf16 v[0:3], v[128:131], v[16:19], v[0:3]
	v_mfma_f32_16x16x32_bf16 v[0:3], v[128:131], v[20:23], v[0:3]
	ds_read_b128 v[16:19], v155 offset:1792
	ds_read_b128 v[20:23], v155 offset:34816
	s_waitcnt vmcnt(4) lgkmcnt(2)
	v_mfma_f32_16x16x32_bf16 v[0:3], v[132:135], v[162:165], v[0:3]
	v_mfma_f32_16x16x32_bf16 v[0:3], v[132:135], v[166:169], v[0:3]
	ds_read_b128 v[162:165], v155 offset:1856
	ds_read_b128 v[166:169], v155 offset:34880
	s_waitcnt vmcnt(3) lgkmcnt(2)
	v_mfma_f32_16x16x32_bf16 v[0:3], v[136:139], v[16:19], v[0:3]
	v_mfma_f32_16x16x32_bf16 v[0:3], v[136:139], v[20:23], v[0:3]
	ds_read_b128 v[16:19], v155 offset:1920
	ds_read_b128 v[20:23], v155 offset:34944
	s_waitcnt vmcnt(2) lgkmcnt(2)
	v_mfma_f32_16x16x32_bf16 v[0:3], v[140:143], v[162:165], v[0:3]
	v_mfma_f32_16x16x32_bf16 v[0:3], v[140:143], v[166:169], v[0:3]
	ds_read_b128 v[162:165], v155 offset:1984
	ds_read_b128 v[166:169], v155 offset:35008
	s_waitcnt vmcnt(1) lgkmcnt(2)
	v_mfma_f32_16x16x32_bf16 v[0:3], v[144:147], v[16:19], v[0:3]
	v_mfma_f32_16x16x32_bf16 v[0:3], v[144:147], v[20:23], v[0:3]
	s_waitcnt vmcnt(0) lgkmcnt(0)
	v_mfma_f32_16x16x32_bf16 v[0:3], v[148:151], v[162:165], v[0:3]
	v_mfma_f32_16x16x32_bf16 v[0:3], v[148:151], v[166:169], v[0:3]
	s_mov_b64 s[4:5], 0x800
	v_lshl_add_u64 v[10:11], v[10:11], 0, s[4:5]
	s_mov_b64 s[4:5], 0x200
	s_movk_i32 s0, 0x800
	s_cmpk_lg_i32 s0, 0x800
	s_nop 6
	ds_bpermute_b32 v9, v156, v0
	v_max_f32_e32 v10, v0, v0
	v_max_f32_e32 v11, v1, v1
	v_max_f32_e32 v14, v2, v2
	v_max_f32_e32 v15, v3, v3
	s_waitcnt lgkmcnt(0)
	v_max_f32_e32 v9, v9, v9
	v_max_f32_e32 v9, v10, v9
	ds_bpermute_b32 v10, v157, v9
	s_add_i32 s12, s12, s79
	s_waitcnt lgkmcnt(0)
	v_max_f32_e32 v10, v10, v10
	v_max_f32_e32 v9, v9, v10
	ds_bpermute_b32 v10, v158, v9
	s_waitcnt lgkmcnt(0)
; #define LAS __attribute__((address_space(3)))
; #define REPS(j) for (int rep_ = 0; rep_ < (((DBLMASK >> (j)) & 1) ? 2 : 1); ++rep_)
; __device__ __forceinline__ void ln1_router_tile(KArgs A, int l, int tile, int lane, const LAS bf16_t* wH) {
;     ...
;     f32x4 p;
; #pragma unroll
;     for (int q = 0; q < 4; ++q) { float x = acc[q], mx = x;
; #pragma unroll
;         for (int o = 1; o < 16; o <<= 1) mx = fmaxf(mx, __shfl_xor(mx, o));
;         const float ex = __expf(x - mx); float se = ex;
; #pragma unroll
;         for (int o = 1; o < 16; o <<= 1) se += __shfl_xor(se, o);
;         p[q] = ex / se; }
;     const int b = t0 >> 12, s0 = t0 & (S_ - 1);
;     *(f32x4*)((float*)(ws + WS_AFF) + ((size_t)(b * NE + (lane & 15))) * S_ + s0 + 4 * (lane >> 4)) = p;
; __global__ void __launch_bounds__(512, 2) fwd_megakernel(Args AV) {
;     ...
;             REPS(5) for (int tile = gw; tile < T_ / 16; tile += NGW) ln1_router_tile(A, l, tile, lane, (const LAS bf16_t*)lds);
	v_max_f32_e32 v10, v10, v10
	v_max_f32_e32 v9, v9, v10
	ds_bpermute_b32 v10, v159, v9
	s_waitcnt lgkmcnt(0)
	v_max_f32_e32 v10, v10, v10
	v_max_f32_e32 v9, v9, v10
	v_sub_f32_e32 v0, v0, v9
	ds_bpermute_b32 v9, v156, v1
	v_mul_f32_e32 v0, 0x3fb8aa3b, v0
	v_exp_f32_e32 v0, v0
	s_waitcnt lgkmcnt(0)
	v_max_f32_e32 v9, v9, v9
	v_max_f32_e32 v9, v11, v9
	ds_bpermute_b32 v11, v157, v9
	ds_bpermute_b32 v10, v156, v0
	s_waitcnt lgkmcnt(1)
	v_max_f32_e32 v11, v11, v11
	v_max_f32_e32 v9, v9, v11
	ds_bpermute_b32 v11, v158, v9
	s_waitcnt lgkmcnt(0)
	v_max_f32_e32 v11, v11, v11
	v_max_f32_e32 v9, v9, v11
	ds_bpermute_b32 v11, v159, v9
	s_waitcnt lgkmcnt(0)
	v_max_f32_e32 v11, v11, v11
	v_max_f32_e32 v9, v9, v11
	v_sub_f32_e32 v1, v1, v9
	ds_bpermute_b32 v9, v156, v2
	v_mul_f32_e32 v1, 0x3fb8aa3b, v1
	v_exp_f32_e32 v1, v1
	s_waitcnt lgkmcnt(0)
	v_max_f32_e32 v9, v9, v9
	v_max_f32_e32 v9, v14, v9
	ds_bpermute_b32 v14, v157, v9
	ds_bpermute_b32 v11, v156, v1
	s_waitcnt lgkmcnt(1)
	v_max_f32_e32 v14, v14, v14
	v_max_f32_e32 v9, v9, v14
	ds_bpermute_b32 v14, v158, v9
	s_waitcnt lgkmcnt(1)
	v_pk_add_f32 v[10:11], v[0:1], v[10:11]
	ds_bpermute_b32 v12, v157, v10
	ds_bpermute_b32 v13, v157, v11
	s_waitcnt lgkmcnt(2)
	v_max_f32_e32 v14, v14, v14
	v_max_f32_e32 v9, v9, v14
	ds_bpermute_b32 v14, v159, v9
	s_waitcnt lgkmcnt(1)
	v_pk_add_f32 v[10:11], v[10:11], v[12:13]
	ds_bpermute_b32 v12, v158, v10
	ds_bpermute_b32 v13, v158, v11
	s_waitcnt lgkmcnt(2)
	v_max_f32_e32 v14, v14, v14
	v_max_f32_e32 v9, v9, v14
	v_sub_f32_e32 v2, v2, v9
	ds_bpermute_b32 v9, v156, v3
	v_mul_f32_e32 v2, 0x3fb8aa3b, v2
	v_exp_f32_e32 v2, v2
	s_waitcnt lgkmcnt(1)
	v_pk_add_f32 v[10:11], v[10:11], v[12:13]
	ds_bpermute_b32 v12, v159, v10
	s_waitcnt lgkmcnt(1)
	v_max_f32_e32 v9, v9, v9
	v_max_f32_e32 v9, v15, v9
	ds_bpermute_b32 v15, v157, v9
	ds_bpermute_b32 v14, v156, v2
	ds_bpermute_b32 v13, v159, v11
	s_waitcnt lgkmcnt(2)
	v_max_f32_e32 v15, v15, v15
	v_max_f32_e32 v9, v9, v15
	ds_bpermute_b32 v15, v158, v9
	s_waitcnt lgkmcnt(1)
	v_pk_add_f32 v[10:11], v[10:11], v[12:13]
	s_waitcnt lgkmcnt(0)
	v_max_f32_e32 v15, v15, v15
	v_max_f32_e32 v9, v9, v15
	ds_bpermute_b32 v15, v159, v9
	s_waitcnt lgkmcnt(0)
	v_max_f32_e32 v15, v15, v15
	v_max_f32_e32 v9, v9, v15
	v_sub_f32_e32 v3, v3, v9
	v_mul_f32_e32 v3, 0x3fb8aa3b, v3
	v_exp_f32_e32 v3, v3
	ds_bpermute_b32 v15, v156, v3
	s_waitcnt lgkmcnt(0)
	v_pk_add_f32 v[14:15], v[2:3], v[14:15]
	ds_bpermute_b32 v16, v157, v14
	ds_bpermute_b32 v17, v157, v15
	s_waitcnt lgkmcnt(0)
	v_pk_add_f32 v[14:15], v[14:15], v[16:17]
	ds_bpermute_b32 v16, v158, v14
	ds_bpermute_b32 v17, v158, v15
	s_waitcnt lgkmcnt(0)
	v_pk_add_f32 v[14:15], v[14:15], v[16:17]
	ds_bpermute_b32 v16, v159, v14
	ds_bpermute_b32 v17, v159, v15
	s_waitcnt lgkmcnt(0)
	v_pk_add_f32 v[12:13], v[14:15], v[16:17]
	s_nop 0
	v_div_scale_f32 v9, s[0:1], v13, v13, v3
	v_rcp_f32_e32 v14, v9
	s_nop 0
	v_fma_f32 v15, -v9, v14, 1.0
	v_fmac_f32_e32 v14, v15, v14
	v_div_scale_f32 v15, vcc, v3, v13, v3
	v_mul_f32_e32 v16, v15, v14
	v_fma_f32 v17, -v9, v16, v15
	v_fmac_f32_e32 v16, v17, v14
	v_fma_f32 v9, -v9, v16, v15
	v_div_fmas_f32 v9, v9, v14, v16
	v_div_fixup_f32 v3, v9, v13, v3
	v_div_scale_f32 v9, s[0:1], v12, v12, v2
	v_rcp_f32_e32 v13, v9
	s_nop 0
	v_fma_f32 v14, -v9, v13, 1.0
	v_fmac_f32_e32 v13, v14, v13
	v_div_scale_f32 v14, vcc, v2, v12, v2
	v_mul_f32_e32 v15, v14, v13
	v_fma_f32 v16, -v9, v15, v14
	v_fmac_f32_e32 v15, v16, v13
	v_fma_f32 v9, -v9, v15, v14
	v_div_fmas_f32 v9, v9, v13, v15
	v_div_fixup_f32 v2, v9, v12, v2
	v_div_scale_f32 v9, s[0:1], v11, v11, v1
	v_rcp_f32_e32 v12, v9
	s_nop 0
	v_fma_f32 v13, -v9, v12, 1.0
	v_fmac_f32_e32 v12, v13, v12
	v_div_scale_f32 v13, vcc, v1, v11, v1
	v_mul_f32_e32 v14, v13, v12
	v_fma_f32 v15, -v9, v14, v13
	v_fmac_f32_e32 v14, v15, v12
	v_fma_f32 v9, -v9, v14, v13
	v_div_fmas_f32 v9, v9, v12, v14
	v_div_fixup_f32 v1, v9, v11, v1
	v_div_scale_f32 v9, s[0:1], v10, v10, v0
	v_rcp_f32_e32 v11, v9
	s_ashr_i32 s1, s22, 4
	s_and_b32 s0, s14, 0xff0
	s_lshl_b32 s86, s0, 2
	v_fma_f32 v12, -v9, v11, 1.0
	v_fmac_f32_e32 v11, v12, v11
	v_div_scale_f32 v12, vcc, v0, v10, v0
	v_mul_f32_e32 v13, v12, v11
	v_fma_f32 v14, -v9, v13, v12
	v_fmac_f32_e32 v13, v14, v11
	v_fma_f32 v9, -v9, v13, v12
	v_div_fmas_f32 v9, v9, v11, v13
	v_div_fixup_f32 v0, v9, v10, v0
	v_and_or_b32 v10, s1, -16, v154
	v_ashrrev_i32_e32 v11, 31, v10
	v_lshlrev_b64 v[10:11], 14, v[10:11]
	v_lshl_add_u64 v[10:11], s[10:11], 0, v[10:11]
	v_readlane_b32 s0, v254, 7
	v_lshl_add_u64 v[10:11], v[10:11], 0, s[86:87]
	v_mov_b32_e32 v9, v195
	s_add_i32 s22, s22, s0
	v_lshl_add_u64 v[10:11], v[10:11], 0, v[8:9]
	s_cmpk_gt_i32 s22, 0x7ff
	global_store_dwordx4 v[10:11], v[0:3], off
	v_readlane_b32 s1, v254, 8
	s_cbranch_scc0 .LBB0_583
